# dead zero-inits before full-row DPP rotates removed in the two conv+gelu FFN-up epilogues (VALU-bound); on top of pipelined prep/final-norm row loops and NA score-modifier rewrite
# speedup vs baseline: 1.0074x; 1.0074x over previous
; #define LAS __attribute__((address_space(3)))
;     __device__ __forceinline__ void operator()(f32x4 (&acc)[2][2][4][2], const Unit& u, int wr, int wc, int fr, int fq) const {
;     ...
;         for (int ai = 0; ai < 2; ++ai)
; #pragma unroll
;             for (int m = 0; m < 4; ++m) { const float rs = RS[wr * 64 + fr + ai * HALF + m * 16];
; #pragma unroll
;                 for (int bj = 0; bj < 2; ++bj)
; #pragma unroll
;                     for (int n = 0; n < 2; ++n) acc[ai][bj][m][n] *= rs; }
;         LAS float* XF = X; LAS float* XL = X + 4 * 128;
; #pragma unroll
;         for (int ai = 0; ai < 2; ++ai) { const int rb = 2 * ai + wr;
;             if (fr == 0) { *(LAS f32x4*)(XF + rb * 128 + cl) = acc[ai][0][0][0]; *(LAS f32x4*)(XF + rb * 128 + cl + 4) = acc[ai][0][0][1]; }
;             if (fr == 15) { *(LAS f32x4*)(XL + rb * 128 + cl) = acc[ai][0][3][0]; *(LAS f32x4*)(XL + rb * 128 + cl + 4) = acc[ai][0][3][1]; } }
;         asm volatile("s_waitcnt lgkmcnt(0)" ::: "memory"); __builtin_amdgcn_s_barrier(); asm volatile("" ::: "memory");
; #pragma unroll
;         for (int ai = 0; ai < 2; ++ai) {
;             const int rb = 2 * ai + wr;
;             f32x4 Sprev[2], Scur[2], Tcur[2], Tnext[2];
; #pragma unroll
;             for (int n = 0; n < 2; ++n) { Sprev[n] = (rb > 0) ? *(const LAS f32x4*)(XL + (rb - 1) * 128 + cl + 4 * n) : (f32x4){0.f, 0.f, 0.f, 0.f};
; #pragma unroll
;                 for (int j = 0; j < 4; ++j) Tcur[n][j] = dpp_rol1(acc[ai][0][0][n][j]); }
; #pragma unroll
;             for (int m = 0; m < 4; ++m) {
; #pragma unroll
;                 for (int n = 0; n < 2; ++n) {
; #pragma unroll
;                     for (int j = 0; j < 4; ++j) Scur[n][j] = dpp_ror1(acc[ai][0][m][n][j]);
;                     if (m < 3) {
; #pragma unroll
;                         for (int j = 0; j < 4; ++j) Tnext[n][j] = dpp_rol1(acc[ai][0][m < 3 ? m + 1 : 3][n][j]);
;                     } else Tnext[n] = (rb < 3) ? *(const LAS f32x4*)(XF + (rb + 1) * 128 + cl + 4 * n) : (f32x4){0.f, 0.f, 0.f, 0.f};
;                 }
;                 const int row = row0 + ai * HALF + m * 16, lrow = row & 255;
;                 const bool edge = (lrow == 0) || (lrow == 255);
;                 u32x4 ow;
; #pragma unroll
;                 for (int n = 0; n < 2; ++n) {
;                     const f32x4 up = (fr == 0) ? Sprev[n] : Scur[n], dn = (fr == 15) ? Tnext[n] : Tcur[n];
.LBB0_1112:
	v_mov_b32_dpp v209, v160 row_ror:15 row_mask:0xf bank_mask:0xf
	v_mov_b32_dpp v244, v161 row_ror:15 row_mask:0xf bank_mask:0xf
	v_mov_b32_dpp v245, v162 row_ror:15 row_mask:0xf bank_mask:0xf
	v_mov_b32_dpp v246, v163 row_ror:15 row_mask:0xf bank_mask:0xf
	s_and_b64 vcc, exec, s[14:15]
	v_mov_b32_e32 v153, 0
	v_mov_b32_e32 v154, 0
	v_mov_b32_e32 v155, 0
	s_cbranch_vccnz .LBB0_1114
	ds_read_b128 v[152:155], v224 offset:16
.LBB0_1114:
	v_pk_mul_f32 v[172:173], v[148:149], v[208:209] op_sel_hi:[1,0]
	v_mov_b32_dpp v236, v160 row_ror:1 row_mask:0xf bank_mask:0xf
	v_mov_b32_dpp v237, v161 row_ror:1 row_mask:0xf bank_mask:0xf
	v_pk_mul_f32 v[148:149], v[146:147], v[208:209] op_sel_hi:[1,0]
	s_waitcnt lgkmcnt(0)
	v_cndmask_b32_e64 v147, v237, v157, s[2:3]
	v_cndmask_b32_e64 v146, v236, v156, s[2:3]
	v_mov_b32_e32 v170, v210
	v_mov_b32_e32 v171, v210
	v_mov_b32_dpp v239, v162 row_ror:1 row_mask:0xf bank_mask:0xf
	v_mov_b32_dpp v241, v163 row_ror:1 row_mask:0xf bank_mask:0xf
	v_mov_b32_dpp v238, v172 row_ror:15 row_mask:0xf bank_mask:0xf
	v_mov_b32_dpp v240, v173 row_ror:15 row_mask:0xf bank_mask:0xf
	v_pk_mul_f32 v[146:147], v[84:85], v[146:147]
	v_pk_mul_f32 v[142:143], v[142:143], v[170:171]
	v_pk_mul_f32 v[138:139], v[138:139], v[170:171]
	v_pk_mul_f32 v[170:171], v[150:151], v[208:209] op_sel_hi:[1,0]
	v_pk_mul_f32 v[150:151], v[144:145], v[208:209] op_sel_hi:[1,0]
	v_cndmask_b32_e64 v145, v241, v159, s[2:3]
	v_cndmask_b32_e64 v144, v239, v158, s[2:3]
	v_cndmask_b32_e64 v159, v244, v240, s[4:5]
	v_cndmask_b32_e64 v158, v209, v238, s[4:5]
	v_pk_fma_f32 v[146:147], v[80:81], v[160:161], v[146:147]
	v_pk_fma_f32 v[146:147], v[68:69], v[158:159], v[146:147]
	v_pk_add_f32 v[146:147], v[76:77], v[146:147]
	v_mov_b32_dpp v242, v170 row_ror:15 row_mask:0xf bank_mask:0xf
	v_mul_f32_e32 v158, v146, v146
	v_fmamk_f32 v158, v158, 0xbdd2d3e7, v232
	v_mul_f32_e32 v159, v147, v147
	v_mul_f32_e32 v158, v146, v158
	v_fmamk_f32 v159, v159, 0xbdd2d3e7, v232
	v_exp_f32_e32 v158, v158
	v_mul_f32_e32 v159, v147, v159
	v_exp_f32_e32 v159, v159
	v_mov_b32_dpp v243, v171 row_ror:15 row_mask:0xf bank_mask:0xf
	v_pk_mul_f32 v[144:145], v[86:87], v[144:145]
	v_cndmask_b32_e64 v157, v246, v243, s[4:5]
	v_cndmask_b32_e64 v156, v245, v242, s[4:5]
	v_pk_fma_f32 v[144:145], v[82:83], v[162:163], v[144:145]
	v_pk_fma_f32 v[144:145], v[70:71], v[156:157], v[144:145]
	v_add_f32_e32 v156, 1.0, v158
	v_rcp_f32_e32 v158, v156
	v_add_f32_e32 v156, 1.0, v159
	v_rcp_f32_e32 v159, v156
	v_pk_add_f32 v[156:157], v[78:79], v[144:145]
	v_mul_f32_e32 v144, v146, v158
	v_mul_f32_e32 v146, v156, v156
	v_mul_f32_e32 v145, v147, v159
	v_mul_f32_e32 v147, v157, v157
	v_fmamk_f32 v146, v146, 0xbdd2d3e7, v232
	v_fmamk_f32 v147, v147, 0xbdd2d3e7, v232
	v_mul_f32_e32 v146, v156, v146
	v_mul_f32_e32 v147, v157, v147
	v_exp_f32_e32 v146, v146
	v_exp_f32_e32 v147, v147
	v_mov_b32_dpp v175, v164 row_ror:1 row_mask:0xf bank_mask:0xf
	v_add_f32_e32 v146, 1.0, v146
	v_add_f32_e32 v147, 1.0, v147
	v_rcp_f32_e32 v146, v146
	v_rcp_f32_e32 v147, v147
	v_mov_b32_dpp v199, v165 row_ror:1 row_mask:0xf bank_mask:0xf
	v_pk_mul_f32 v[140:141], v[140:141], v[210:211]
	v_pk_mul_f32 v[136:137], v[136:137], v[210:211]
	v_cndmask_b32_e64 v153, v199, v153, s[2:3]
	v_cndmask_b32_e64 v152, v175, v152, s[2:3]
	v_mov_b32_dpp v247, v164 row_ror:15 row_mask:0xf bank_mask:0xf
	v_mov_b32_dpp v248, v165 row_ror:15 row_mask:0xf bank_mask:0xf
	v_mov_b32_dpp v201, v150 row_ror:15 row_mask:0xf bank_mask:0xf
	v_mov_b32_dpp v210, v151 row_ror:15 row_mask:0xf bank_mask:0xf
	v_mul_f32_e32 v144, v140, v144
	v_mul_f32_e32 v145, v141, v145
	v_pk_mul_f32 v[152:153], v[44:45], v[152:153]
	v_cvt_pk_bf16_f32 v144, v144, v145
	v_mul_f32_e32 v145, v156, v146
	v_mul_f32_e32 v146, v157, v147
	v_cndmask_b32_e64 v157, v248, v210, s[4:5]
	v_cndmask_b32_e64 v156, v247, v201, s[4:5]
	v_pk_fma_f32 v[152:153], v[40:41], v[164:165], v[152:153]
	v_pk_fma_f32 v[152:153], v[32:33], v[156:157], v[152:153]
	v_pk_add_f32 v[152:153], v[36:37], v[152:153]
	v_mov_b32_dpp v207, v166 row_ror:1 row_mask:0xf bank_mask:0xf
	v_mul_f32_e32 v156, v152, v152
	v_fmamk_f32 v156, v156, 0xbdd2d3e7, v232
	v_mul_f32_e32 v157, v153, v153
	v_mul_f32_e32 v156, v152, v156
	v_fmamk_f32 v157, v157, 0xbdd2d3e7, v232
	v_mov_b32_dpp v211, v167 row_ror:1 row_mask:0xf bank_mask:0xf
	v_mul_f32_e32 v145, v142, v145
	v_mul_f32_e32 v146, v143, v146
	v_exp_f32_e32 v156, v156
	v_mul_f32_e32 v157, v153, v157
	v_cvt_pk_bf16_f32 v145, v145, v146
	v_cndmask_b32_e64 v147, v211, v155, s[2:3]
	v_cndmask_b32_e64 v146, v207, v154, s[2:3]
	v_exp_f32_e32 v157, v157
	v_mov_b32_dpp v249, v166 row_ror:15 row_mask:0xf bank_mask:0xf
	v_mov_b32_dpp v250, v167 row_ror:15 row_mask:0xf bank_mask:0xf
	v_mov_b32_dpp v234, v148 row_ror:15 row_mask:0xf bank_mask:0xf
	v_mov_b32_dpp v235, v149 row_ror:15 row_mask:0xf bank_mask:0xf
	v_pk_mul_f32 v[146:147], v[46:47], v[146:147]
	v_cndmask_b32_e64 v155, v250, v235, s[4:5]
	v_cndmask_b32_e64 v154, v249, v234, s[4:5]
	v_pk_fma_f32 v[146:147], v[42:43], v[166:167], v[146:147]
	v_or_b32_e32 v168, s52, v214
	v_pk_fma_f32 v[146:147], v[34:35], v[154:155], v[146:147]
	v_add_f32_e32 v154, 1.0, v156
	v_rcp_f32_e32 v156, v154
	v_add_f32_e32 v154, 1.0, v157
	v_rcp_f32_e32 v157, v154
	v_pk_add_f32 v[154:155], v[38:39], v[146:147]
	v_mul_f32_e32 v146, v152, v156
	v_mul_f32_e32 v152, v154, v154
	v_mul_f32_e32 v147, v153, v157
	v_fmamk_f32 v152, v152, 0xbdd2d3e7, v232
	v_mul_f32_e32 v153, v155, v155
	v_mul_f32_e32 v152, v154, v152
	v_fmamk_f32 v153, v153, 0xbdd2d3e7, v232
	v_exp_f32_e32 v152, v152
	v_mul_f32_e32 v153, v155, v153
	v_exp_f32_e32 v153, v153
	v_mul_f32_e32 v146, v136, v146
	v_add_f32_e32 v152, 1.0, v152
	v_rcp_f32_e32 v152, v152
	v_add_f32_e32 v153, 1.0, v153
	v_rcp_f32_e32 v153, v153
	v_mul_f32_e32 v147, v137, v147
	v_cvt_pk_bf16_f32 v146, v146, v147
	v_mul_f32_e32 v147, v154, v152
	v_ashrrev_i32_e32 v169, 31, v168
	v_add_u32_e32 v174, s19, v212
	v_mul_f32_e32 v147, v138, v147
	v_mul_f32_e32 v152, v155, v153
	v_mul_f32_e32 v152, v139, v152
	v_cvt_pk_bf16_f32 v147, v147, v152
	s_and_saveexec_b64 s[14:15], s[8:9]
	s_cbranch_execz .LBB0_1116
	v_readlane_b32 s52, v254, 15
	v_readlane_b32 s53, v254, 16
	s_nop 1
	v_mov_b64_e32 v[152:153], s[52:53]
	v_mad_i64_i32 v[152:153], s[52:53], v174, s75, v[152:153]
	v_lshl_add_u64 v[152:153], v[168:169], 1, v[152:153]
	global_store_dwordx4 v[152:153], v[144:147], off

; #define LAS __attribute__((address_space(3)))
;     __device__ __forceinline__ void operator()(f32x4 (&acc)[2][2][4][2], const Unit& u, int wr, int wc, int fr, int fq) const {
;     ...
;         for (int ai = 0; ai < 2; ++ai)
; #pragma unroll
;             for (int m = 0; m < 4; ++m) { const float rs = RS[wr * 64 + fr + ai * HALF + m * 16];
; #pragma unroll
;                 for (int bj = 0; bj < 2; ++bj)
; #pragma unroll
;                     for (int n = 0; n < 2; ++n) acc[ai][bj][m][n] *= rs; }
;         LAS float* XF = X; LAS float* XL = X + 4 * 128;
; #pragma unroll
;         for (int ai = 0; ai < 2; ++ai) { const int rb = 2 * ai + wr;
;             if (fr == 0) { *(LAS f32x4*)(XF + rb * 128 + cl) = acc[ai][0][0][0]; *(LAS f32x4*)(XF + rb * 128 + cl + 4) = acc[ai][0][0][1]; }
;             if (fr == 15) { *(LAS f32x4*)(XL + rb * 128 + cl) = acc[ai][0][3][0]; *(LAS f32x4*)(XL + rb * 128 + cl + 4) = acc[ai][0][3][1]; } }
;         asm volatile("s_waitcnt lgkmcnt(0)" ::: "memory"); __builtin_amdgcn_s_barrier(); asm volatile("" ::: "memory");
; #pragma unroll
;         for (int ai = 0; ai < 2; ++ai) {
;             const int rb = 2 * ai + wr;
;             f32x4 Sprev[2], Scur[2], Tcur[2], Tnext[2];
; #pragma unroll
;             for (int n = 0; n < 2; ++n) { Sprev[n] = (rb > 0) ? *(const LAS f32x4*)(XL + (rb - 1) * 128 + cl + 4 * n) : (f32x4){0.f, 0.f, 0.f, 0.f};
; #pragma unroll
;                 for (int j = 0; j < 4; ++j) Tcur[n][j] = dpp_rol1(acc[ai][0][0][n][j]); }
; #pragma unroll
;             for (int m = 0; m < 4; ++m) {
; #pragma unroll
;                 for (int n = 0; n < 2; ++n) {
; #pragma unroll
;                     for (int j = 0; j < 4; ++j) Scur[n][j] = dpp_ror1(acc[ai][0][m][n][j]);
;                     if (m < 3) {
; #pragma unroll
;                         for (int j = 0; j < 4; ++j) Tnext[n][j] = dpp_rol1(acc[ai][0][m < 3 ? m + 1 : 3][n][j]);
;                     } else Tnext[n] = (rb < 3) ? *(const LAS f32x4*)(XF + (rb + 1) * 128 + cl + 4 * n) : (f32x4){0.f, 0.f, 0.f, 0.f};
;                 }
;                 const int row = row0 + ai * HALF + m * 16, lrow = row & 255;
;                 const bool edge = (lrow == 0) || (lrow == 255);
;                 u32x4 ow;
; #pragma unroll
;                 for (int n = 0; n < 2; ++n) {
;                     const f32x4 up = (fr == 0) ? Sprev[n] : Scur[n], dn = (fr == 15) ? Tnext[n] : Tcur[n];
.LBB0_1119:
	s_or_b64 exec, exec, s[14:15]
	v_mov_b32_e32 v136, v208
	v_mov_b32_e32 v137, v208
	v_mov_b32_dpp v152, v172 row_ror:1 row_mask:0xf bank_mask:0xf
	v_mov_b32_dpp v153, v173 row_ror:1 row_mask:0xf bank_mask:0xf
	v_pk_mul_f32 v[138:139], v[118:119], v[136:137]
	v_pk_mul_f32 v[136:137], v[114:115], v[136:137]
	v_pk_mul_f32 v[124:125], v[124:125], v[206:207] op_sel_hi:[1,0]
	v_pk_mul_f32 v[114:115], v[122:123], v[206:207] op_sel_hi:[1,0]
	v_cndmask_b32_e64 v123, v153, v237, s[2:3]
	v_cndmask_b32_e64 v122, v152, v236, s[2:3]
	v_mov_b32_dpp v156, v124 row_ror:15 row_mask:0xf bank_mask:0xf
	v_mov_b32_dpp v157, v125 row_ror:15 row_mask:0xf bank_mask:0xf
	v_pk_mul_f32 v[122:123], v[84:85], v[122:123]
	v_cndmask_b32_e64 v143, v240, v157, s[4:5]
	v_cndmask_b32_e64 v142, v238, v156, s[4:5]
	v_pk_fma_f32 v[122:123], v[80:81], v[172:173], v[122:123]
	v_pk_fma_f32 v[122:123], v[68:69], v[142:143], v[122:123]
	v_pk_add_f32 v[122:123], v[76:77], v[122:123]
	v_mov_b32_e32 v209, v208
	v_mul_f32_e32 v142, v122, v122
	v_fmamk_f32 v142, v142, 0xbdd2d3e7, v232
	v_mul_f32_e32 v143, v123, v123
	v_mul_f32_e32 v142, v122, v142
	v_fmamk_f32 v143, v143, 0xbdd2d3e7, v232
	v_mov_b32_dpp v154, v170 row_ror:1 row_mask:0xf bank_mask:0xf
	v_mov_b32_dpp v155, v171 row_ror:1 row_mask:0xf bank_mask:0xf
	v_exp_f32_e32 v142, v142
	v_mul_f32_e32 v143, v123, v143
	v_pk_mul_f32 v[140:141], v[116:117], v[208:209]
	v_pk_mul_f32 v[118:119], v[126:127], v[206:207] op_sel_hi:[1,0]
	v_pk_mul_f32 v[116:117], v[120:121], v[206:207] op_sel_hi:[1,0]
	v_cndmask_b32_e64 v121, v155, v241, s[2:3]
	v_cndmask_b32_e64 v120, v154, v239, s[2:3]
	v_exp_f32_e32 v143, v143
	v_mov_b32_dpp v158, v118 row_ror:15 row_mask:0xf bank_mask:0xf
	v_mov_b32_dpp v159, v119 row_ror:15 row_mask:0xf bank_mask:0xf
	v_pk_mul_f32 v[120:121], v[86:87], v[120:121]
	v_cndmask_b32_e64 v127, v243, v159, s[4:5]
	v_cndmask_b32_e64 v126, v242, v158, s[4:5]
	v_pk_fma_f32 v[120:121], v[82:83], v[170:171], v[120:121]
	v_pk_fma_f32 v[120:121], v[70:71], v[126:127], v[120:121]
	v_add_f32_e32 v126, 1.0, v142
	v_rcp_f32_e32 v142, v126
	v_add_f32_e32 v126, 1.0, v143
	v_rcp_f32_e32 v143, v126
	v_pk_add_f32 v[126:127], v[78:79], v[120:121]
	v_mul_f32_e32 v120, v122, v142
	v_mul_f32_e32 v122, v126, v126
	v_mul_f32_e32 v121, v123, v143
	v_mul_f32_e32 v123, v127, v127
	v_fmamk_f32 v122, v122, 0xbdd2d3e7, v232
	v_fmamk_f32 v123, v123, 0xbdd2d3e7, v232
	v_mul_f32_e32 v122, v126, v122
	v_mul_f32_e32 v123, v127, v123
	v_exp_f32_e32 v122, v122
	v_exp_f32_e32 v123, v123
	v_mov_b32_dpp v160, v150 row_ror:1 row_mask:0xf bank_mask:0xf
	v_add_f32_e32 v122, 1.0, v122
	v_add_f32_e32 v123, 1.0, v123
	v_rcp_f32_e32 v122, v122
	v_rcp_f32_e32 v123, v123
	v_mov_b32_dpp v161, v151 row_ror:1 row_mask:0xf bank_mask:0xf
	v_mul_f32_e32 v120, v140, v120
	v_mul_f32_e32 v121, v141, v121
	v_cvt_pk_bf16_f32 v120, v120, v121
	v_mul_f32_e32 v121, v126, v122
	v_mul_f32_e32 v122, v127, v123
	v_cndmask_b32_e64 v127, v161, v199, s[2:3]
	v_cndmask_b32_e64 v126, v160, v175, s[2:3]
	v_mov_b32_dpp v164, v116 row_ror:15 row_mask:0xf bank_mask:0xf
	v_mov_b32_dpp v165, v117 row_ror:15 row_mask:0xf bank_mask:0xf
	v_pk_mul_f32 v[126:127], v[44:45], v[126:127]
	v_cndmask_b32_e64 v141, v210, v165, s[4:5]
	v_cndmask_b32_e64 v140, v201, v164, s[4:5]
	v_pk_fma_f32 v[126:127], v[40:41], v[150:151], v[126:127]
	v_pk_fma_f32 v[126:127], v[32:33], v[140:141], v[126:127]
	v_pk_add_f32 v[126:127], v[36:37], v[126:127]
	v_mov_b32_dpp v162, v148 row_ror:1 row_mask:0xf bank_mask:0xf
	v_mul_f32_e32 v140, v126, v126
	v_fmamk_f32 v140, v140, 0xbdd2d3e7, v232
	v_mul_f32_e32 v140, v126, v140
	v_mul_f32_e32 v141, v127, v127
	v_mov_b32_dpp v163, v149 row_ror:1 row_mask:0xf bank_mask:0xf
	v_mul_f32_e32 v121, v138, v121
	v_mul_f32_e32 v122, v139, v122
	v_exp_f32_e32 v140, v140
	v_fmamk_f32 v141, v141, 0xbdd2d3e7, v232
	v_cvt_pk_bf16_f32 v121, v121, v122
	v_cndmask_b32_e64 v123, v163, v211, s[2:3]
	v_cndmask_b32_e64 v122, v162, v207, s[2:3]
	v_mul_f32_e32 v141, v127, v141
	v_mov_b32_dpp v166, v114 row_ror:15 row_mask:0xf bank_mask:0xf
	v_mov_b32_dpp v167, v115 row_ror:15 row_mask:0xf bank_mask:0xf
	v_pk_mul_f32 v[122:123], v[46:47], v[122:123]
	v_exp_f32_e32 v141, v141
	v_cndmask_b32_e64 v139, v235, v167, s[4:5]
	v_cndmask_b32_e64 v138, v234, v166, s[4:5]
	v_pk_fma_f32 v[122:123], v[42:43], v[148:149], v[122:123]
	v_pk_mul_f32 v[112:113], v[112:113], v[208:209]
	v_pk_fma_f32 v[122:123], v[34:35], v[138:139], v[122:123]
	v_add_f32_e32 v138, 1.0, v140
	v_rcp_f32_e32 v140, v138
	v_add_f32_e32 v138, 1.0, v141
	v_rcp_f32_e32 v141, v138
	v_pk_add_f32 v[138:139], v[38:39], v[122:123]
	v_mul_f32_e32 v122, v126, v140
	v_mul_f32_e32 v123, v138, v138
	v_fmamk_f32 v123, v123, 0xbdd2d3e7, v232
	v_mul_f32_e32 v126, v139, v139
	v_mul_f32_e32 v123, v138, v123
	v_fmamk_f32 v126, v126, 0xbdd2d3e7, v232
	v_exp_f32_e32 v123, v123
	v_mul_f32_e32 v126, v139, v126
	v_exp_f32_e32 v126, v126
	v_mul_f32_e32 v112, v112, v122
	v_mul_f32_e32 v122, v127, v141
	v_mul_f32_e32 v113, v113, v122
	v_add_f32_e32 v122, 1.0, v123
	v_rcp_f32_e32 v123, v122
	v_add_f32_e32 v122, 1.0, v126
	v_rcp_f32_e32 v126, v122
	v_cvt_pk_bf16_f32 v122, v112, v113
	v_mul_f32_e32 v112, v138, v123
	v_mul_f32_e32 v113, v139, v126
	v_mov_b32_dpp v138, v124 row_ror:1 row_mask:0xf bank_mask:0xf
	v_mov_b32_dpp v139, v125 row_ror:1 row_mask:0xf bank_mask:0xf
	v_cndmask_b32_e64 v151, v139, v153, s[2:3]
	v_cndmask_b32_e64 v150, v138, v152, s[2:3]
	v_mov_b32_dpp v141, v118 row_ror:1 row_mask:0xf bank_mask:0xf
	v_mov_b32_dpp v143, v119 row_ror:1 row_mask:0xf bank_mask:0xf
	v_mov_b32_dpp v140, v128 row_ror:15 row_mask:0xf bank_mask:0xf
; #define LAS __attribute__((address_space(3)))
;     __device__ __forceinline__ void operator()(f32x4 (&acc)[2][2][4][2], const Unit& u, int wr, int wc, int fr, int fq) const {
;     ...
;         for (int ai = 0; ai < 2; ++ai)
; #pragma unroll
;             for (int m = 0; m < 4; ++m) { const float rs = RS[wr * 64 + fr + ai * HALF + m * 16];
; #pragma unroll
;                 for (int bj = 0; bj < 2; ++bj)
; #pragma unroll
;                     for (int n = 0; n < 2; ++n) acc[ai][bj][m][n] *= rs; }
;         LAS float* XF = X; LAS float* XL = X + 4 * 128;
; #pragma unroll
;         for (int ai = 0; ai < 2; ++ai) { const int rb = 2 * ai + wr;
;             if (fr == 0) { *(LAS f32x4*)(XF + rb * 128 + cl) = acc[ai][0][0][0]; *(LAS f32x4*)(XF + rb * 128 + cl + 4) = acc[ai][0][0][1]; }
;             if (fr == 15) { *(LAS f32x4*)(XL + rb * 128 + cl) = acc[ai][0][3][0]; *(LAS f32x4*)(XL + rb * 128 + cl + 4) = acc[ai][0][3][1]; } }
;         asm volatile("s_waitcnt lgkmcnt(0)" ::: "memory"); __builtin_amdgcn_s_barrier(); asm volatile("" ::: "memory");
; #pragma unroll
;         for (int ai = 0; ai < 2; ++ai) {
;             const int rb = 2 * ai + wr;
;             f32x4 Sprev[2], Scur[2], Tcur[2], Tnext[2];
; #pragma unroll
;             for (int n = 0; n < 2; ++n) { Sprev[n] = (rb > 0) ? *(const LAS f32x4*)(XL + (rb - 1) * 128 + cl + 4 * n) : (f32x4){0.f, 0.f, 0.f, 0.f};
; #pragma unroll
;                 for (int j = 0; j < 4; ++j) Tcur[n][j] = dpp_rol1(acc[ai][0][0][n][j]); }
; #pragma unroll
;             for (int m = 0; m < 4; ++m) {
; #pragma unroll
;                 for (int n = 0; n < 2; ++n) {
; #pragma unroll
;                     for (int j = 0; j < 4; ++j) Scur[n][j] = dpp_ror1(acc[ai][0][m][n][j]);
;                     if (m < 3) {
; #pragma unroll
;                         for (int j = 0; j < 4; ++j) Tnext[n][j] = dpp_rol1(acc[ai][0][m < 3 ? m + 1 : 3][n][j]);
;                     } else Tnext[n] = (rb < 3) ? *(const LAS f32x4*)(XF + (rb + 1) * 128 + cl + 4 * n) : (f32x4){0.f, 0.f, 0.f, 0.f};
;                 }
;                 const int row = row0 + ai * HALF + m * 16, lrow = row & 255;
;                 const bool edge = (lrow == 0) || (lrow == 255);
;                 u32x4 ow;
; #pragma unroll
;                 for (int n = 0; n < 2; ++n) {
;                     const f32x4 up = (fr == 0) ? Sprev[n] : Scur[n], dn = (fr == 15) ? Tnext[n] : Tcur[n];
	v_mov_b32_dpp v142, v129 row_ror:15 row_mask:0xf bank_mask:0xf
	v_pk_mul_f32 v[150:151], v[84:85], v[150:151]
	v_cndmask_b32_e64 v149, v143, v155, s[2:3]
	v_cndmask_b32_e64 v148, v141, v154, s[2:3]
	v_cndmask_b32_e64 v155, v157, v142, s[4:5]
	v_cndmask_b32_e64 v154, v156, v140, s[4:5]
	v_pk_fma_f32 v[124:125], v[80:81], v[124:125], v[150:151]
	v_pk_mul_f32 v[148:149], v[86:87], v[148:149]
	v_pk_fma_f32 v[124:125], v[68:69], v[154:155], v[124:125]
	v_pk_fma_f32 v[118:119], v[82:83], v[118:119], v[148:149]
	v_pk_add_f32 v[124:125], v[76:77], v[124:125]
	v_readlane_b32 s14, v254, 15
	v_mul_f32_e32 v148, v124, v124
	v_fmamk_f32 v148, v148, 0xbdd2d3e7, v232
	v_mul_f32_e32 v149, v125, v125
	v_mul_f32_e32 v148, v124, v148
	v_fmamk_f32 v149, v149, 0xbdd2d3e7, v232
	v_exp_f32_e32 v148, v148
	v_mul_f32_e32 v149, v125, v149
	v_exp_f32_e32 v149, v149
	v_readlane_b32 s15, v254, 16
	v_or_b32_e32 v144, 16, v174
	v_add_f32_e32 v148, 1.0, v148
	v_mov_b64_e32 v[146:147], s[14:15]
	v_mad_i64_i32 v[126:127], s[14:15], v144, s75, v[146:147]
	v_rcp_f32_e32 v148, v148
	v_add_f32_e32 v149, 1.0, v149
	v_mov_b32_dpp v144, v130 row_ror:15 row_mask:0xf bank_mask:0xf
	v_mov_b32_dpp v145, v131 row_ror:15 row_mask:0xf bank_mask:0xf
	v_rcp_f32_e32 v149, v149
	v_cndmask_b32_e64 v153, v159, v145, s[4:5]
	v_cndmask_b32_e64 v152, v158, v144, s[4:5]
	v_pk_fma_f32 v[118:119], v[70:71], v[152:153], v[118:119]
	v_pk_mul_f32 v[108:109], v[108:109], v[206:207] op_sel_hi:[1,0]
	v_pk_add_f32 v[118:119], v[78:79], v[118:119]
	v_mul_f32_e32 v124, v124, v148
	v_mul_f32_e32 v108, v108, v124
	v_mul_f32_e32 v124, v125, v149
	v_mul_f32_e32 v125, v118, v118
	v_fmamk_f32 v125, v125, 0xbdd2d3e7, v232
	v_mul_f32_e32 v148, v119, v119
	v_mul_f32_e32 v125, v118, v125
	v_fmamk_f32 v148, v148, 0xbdd2d3e7, v232
	v_exp_f32_e32 v125, v125
	v_mul_f32_e32 v148, v119, v148
	v_exp_f32_e32 v148, v148
	v_mul_f32_e32 v109, v109, v124
	v_add_f32_e32 v124, 1.0, v125
	v_rcp_f32_e32 v124, v124
	v_add_f32_e32 v125, 1.0, v148
	v_mul_f32_e32 v112, v136, v112
	v_mul_f32_e32 v113, v137, v113
	v_rcp_f32_e32 v125, v125
	v_cvt_pk_bf16_f32 v123, v112, v113
	v_lshlrev_b64 v[112:113], 1, v[168:169]
	v_lshl_add_u64 v[126:127], v[126:127], 0, v[112:113]
	v_pk_mul_f32 v[110:111], v[110:111], v[206:207] op_sel_hi:[1,0]
	global_store_dwordx4 v[126:127], v[120:123], off
	v_cvt_pk_bf16_f32 v108, v108, v109
	v_mul_f32_e32 v109, v118, v124
	v_mul_f32_e32 v109, v110, v109
	v_mul_f32_e32 v110, v119, v125
	v_mov_b32_dpp v120, v116 row_ror:1 row_mask:0xf bank_mask:0xf
	v_mov_b32_dpp v121, v117 row_ror:1 row_mask:0xf bank_mask:0xf
	v_mov_b32_dpp v123, v114 row_ror:1 row_mask:0xf bank_mask:0xf
	v_mov_b32_dpp v127, v115 row_ror:1 row_mask:0xf bank_mask:0xf
	v_mul_f32_e32 v110, v111, v110
	v_cvt_pk_bf16_f32 v109, v109, v110
	v_cndmask_b32_e64 v111, v127, v163, s[2:3]
	v_cndmask_b32_e64 v110, v123, v162, s[2:3]
	v_cndmask_b32_e64 v119, v121, v161, s[2:3]
	v_cndmask_b32_e64 v118, v120, v160, s[2:3]
	v_mov_b32_dpp v122, v132 row_ror:15 row_mask:0xf bank_mask:0xf
	v_mov_b32_dpp v126, v133 row_ror:15 row_mask:0xf bank_mask:0xf
	v_pk_mul_f32 v[118:119], v[44:45], v[118:119]
	v_pk_mul_f32 v[110:111], v[46:47], v[110:111]
	v_cndmask_b32_e64 v149, v165, v126, s[4:5]
	v_cndmask_b32_e64 v148, v164, v122, s[4:5]
	v_pk_fma_f32 v[110:111], v[42:43], v[114:115], v[110:111]
	v_pk_fma_f32 v[114:115], v[40:41], v[116:117], v[118:119]
	v_pk_fma_f32 v[114:115], v[32:33], v[148:149], v[114:115]
	v_pk_add_f32 v[114:115], v[36:37], v[114:115]
	v_mov_b32_dpp v136, v134 row_ror:15 row_mask:0xf bank_mask:0xf
	v_mul_f32_e32 v116, v114, v114
	v_fmamk_f32 v116, v116, 0xbdd2d3e7, v232
	v_mul_f32_e32 v116, v114, v116
	v_mul_f32_e32 v117, v115, v115
	v_exp_f32_e32 v116, v116
	v_fmamk_f32 v117, v117, 0xbdd2d3e7, v232
	v_mul_f32_e32 v117, v115, v117
	v_exp_f32_e32 v117, v117
	v_mov_b32_dpp v137, v135 row_ror:15 row_mask:0xf bank_mask:0xf
	v_add_f32_e32 v116, 1.0, v116
	v_cndmask_b32_e64 v125, v167, v137, s[4:5]
	v_cndmask_b32_e64 v124, v166, v136, s[4:5]
	v_rcp_f32_e32 v118, v116
	v_pk_fma_f32 v[110:111], v[34:35], v[124:125], v[110:111]
	v_add_f32_e32 v116, 1.0, v117
	v_rcp_f32_e32 v119, v116
	v_pk_add_f32 v[116:117], v[38:39], v[110:111]
	v_mul_f32_e32 v110, v114, v118
	v_mul_f32_e32 v111, v116, v116
	v_fmamk_f32 v111, v111, 0xbdd2d3e7, v232
	v_mul_f32_e32 v114, v117, v117
	v_mul_f32_e32 v111, v116, v111
	v_fmamk_f32 v114, v114, 0xbdd2d3e7, v232
	v_exp_f32_e32 v111, v111
	v_mul_f32_e32 v114, v117, v114
	v_exp_f32_e32 v114, v114
	v_pk_mul_f32 v[104:105], v[104:105], v[206:207] op_sel_hi:[1,0]
	v_pk_mul_f32 v[106:107], v[106:107], v[206:207] op_sel_hi:[1,0]
	v_mul_f32_e32 v104, v104, v110
	v_mul_f32_e32 v110, v115, v119
	v_mul_f32_e32 v105, v105, v110
	v_add_f32_e32 v110, 1.0, v111
	v_rcp_f32_e32 v111, v110
	v_add_f32_e32 v110, 1.0, v114
	v_rcp_f32_e32 v114, v110
	v_cvt_pk_bf16_f32 v110, v104, v105
	v_mul_f32_e32 v104, v116, v111
	v_or_b32_e32 v170, 32, v174
	v_mul_f32_e32 v105, v117, v114
	v_mul_f32_e32 v104, v106, v104
	v_mul_f32_e32 v105, v107, v105
	v_cvt_pk_bf16_f32 v111, v104, v105
	v_mad_i64_i32 v[104:105], s[14:15], v170, s75, v[146:147]
	v_lshl_add_u64 v[104:105], v[104:105], 0, v[112:113]
	global_store_dwordx4 v[104:105], v[108:111], off
	v_cndmask_b32_e64 v105, 0, 1, s[36:37]
	v_mov_b32_dpp v119, v128 row_ror:1 row_mask:0xf bank_mask:0xf
	v_mov_b32_dpp v124, v129 row_ror:1 row_mask:0xf bank_mask:0xf
	v_mov_b32_dpp v125, v130 row_ror:1 row_mask:0xf bank_mask:0xf
	v_mov_b32_dpp v146, v131 row_ror:1 row_mask:0xf bank_mask:0xf
	v_mov_b32_e32 v104, 0
	v_cmp_ne_u32_e64 s[14:15], 1, v105
	s_andn2_b64 vcc, exec, s[36:37]
	v_mov_b32_e32 v108, 0
	v_mov_b32_e32 v109, 0
	v_mov_b32_e32 v110, 0
	v_mov_b32_e32 v111, 0
	s_cbranch_vccnz .LBB0_1121
	ds_read_b128 v[108:111], v225 offset:512
.LBB0_1121:
	v_mov_b32_dpp v115, v132 row_ror:1 row_mask:0xf bank_mask:0xf
	v_mov_b32_dpp v116, v133 row_ror:1 row_mask:0xf bank_mask:0xf
	v_mov_b32_dpp v117, v134 row_ror:1 row_mask:0xf bank_mask:0xf
	v_mov_b32_dpp v118, v135 row_ror:1 row_mask:0xf bank_mask:0xf
	s_and_b64 vcc, exec, s[14:15]
	v_mov_b32_e32 v105, 0
	v_mov_b32_e32 v106, 0
	v_mov_b32_e32 v107, 0
	s_cbranch_vccnz .LBB0_1123
	ds_read_b128 v[104:107], v225 offset:528

; #define LAS __attribute__((address_space(3)))
;     __device__ __forceinline__ void operator()(f32x4 (&acc)[2][2][4][2], const Unit& u, int wr, int wc, int fr, int fq) const {
;     ...
;         for (int ai = 0; ai < 2; ++ai)
; #pragma unroll
;             for (int m = 0; m < 4; ++m) { const float rs = RS[wr * 64 + fr + ai * HALF + m * 16];
; #pragma unroll
;                 for (int bj = 0; bj < 2; ++bj)
; #pragma unroll
;                     for (int n = 0; n < 2; ++n) acc[ai][bj][m][n] *= rs; }
;         LAS float* XF = X; LAS float* XL = X + 4 * 128;
; #pragma unroll
;         for (int ai = 0; ai < 2; ++ai) { const int rb = 2 * ai + wr;
;             if (fr == 0) { *(LAS f32x4*)(XF + rb * 128 + cl) = acc[ai][0][0][0]; *(LAS f32x4*)(XF + rb * 128 + cl + 4) = acc[ai][0][0][1]; }
;             if (fr == 15) { *(LAS f32x4*)(XL + rb * 128 + cl) = acc[ai][0][3][0]; *(LAS f32x4*)(XL + rb * 128 + cl + 4) = acc[ai][0][3][1]; } }
;         asm volatile("s_waitcnt lgkmcnt(0)" ::: "memory"); __builtin_amdgcn_s_barrier(); asm volatile("" ::: "memory");
; #pragma unroll
;         for (int ai = 0; ai < 2; ++ai) {
;             const int rb = 2 * ai + wr;
;             f32x4 Sprev[2], Scur[2], Tcur[2], Tnext[2];
; #pragma unroll
;             for (int n = 0; n < 2; ++n) { Sprev[n] = (rb > 0) ? *(const LAS f32x4*)(XL + (rb - 1) * 128 + cl + 4 * n) : (f32x4){0.f, 0.f, 0.f, 0.f};
; #pragma unroll
;                 for (int j = 0; j < 4; ++j) Tcur[n][j] = dpp_rol1(acc[ai][0][0][n][j]); }
; #pragma unroll
;             for (int m = 0; m < 4; ++m) {
; #pragma unroll
;                 for (int n = 0; n < 2; ++n) {
; #pragma unroll
;                     for (int j = 0; j < 4; ++j) Scur[n][j] = dpp_ror1(acc[ai][0][m][n][j]);
;                     if (m < 3) {
; #pragma unroll
;                         for (int j = 0; j < 4; ++j) Tnext[n][j] = dpp_rol1(acc[ai][0][m < 3 ? m + 1 : 3][n][j]);
;                     } else Tnext[n] = (rb < 3) ? *(const LAS f32x4*)(XF + (rb + 1) * 128 + cl + 4 * n) : (f32x4){0.f, 0.f, 0.f, 0.f};
;                 }
;                 const int row = row0 + ai * HALF + m * 16, lrow = row & 255;
;                 const bool edge = (lrow == 0) || (lrow == 255);
;                 u32x4 ow;
; #pragma unroll
;                 for (int n = 0; n < 2; ++n) {
;                     const f32x4 up = (fr == 0) ? Sprev[n] : Scur[n], dn = (fr == 15) ? Tnext[n] : Tcur[n];
.LBB0_1130:
	v_mov_b32_dpp v128, v96 row_ror:15 row_mask:0xf bank_mask:0xf
	v_mov_b32_dpp v129, v97 row_ror:15 row_mask:0xf bank_mask:0xf
	v_mov_b32_dpp v130, v98 row_ror:15 row_mask:0xf bank_mask:0xf
	v_mov_b32_dpp v131, v99 row_ror:15 row_mask:0xf bank_mask:0xf
	s_and_b64 vcc, exec, s[14:15]
	v_mov_b32_e32 v89, 0
	v_mov_b32_e32 v90, 0
	v_mov_b32_e32 v91, 0
	s_cbranch_vccnz .LBB0_1132
	ds_read_b128 v[88:91], v226 offset:16
.LBB0_1132:
	v_pk_mul_f32 v[106:107], v[72:73], v[200:201] op_sel_hi:[1,0]
	v_mov_b32_dpp v118, v96 row_ror:1 row_mask:0xf bank_mask:0xf
	v_mov_b32_dpp v119, v97 row_ror:1 row_mask:0xf bank_mask:0xf
	v_pk_mul_f32 v[72:73], v[66:67], v[200:201] op_sel_hi:[1,0]
	s_waitcnt lgkmcnt(0)
	v_cndmask_b32_e64 v67, v119, v93, s[2:3]
	v_cndmask_b32_e64 v66, v118, v92, s[2:3]
	v_mov_b32_e32 v104, v202
	v_mov_b32_e32 v105, v202
	v_mov_b32_dpp v121, v98 row_ror:1 row_mask:0xf bank_mask:0xf
	v_mov_b32_dpp v123, v99 row_ror:1 row_mask:0xf bank_mask:0xf
	v_mov_b32_dpp v120, v106 row_ror:15 row_mask:0xf bank_mask:0xf
	v_mov_b32_dpp v122, v107 row_ror:15 row_mask:0xf bank_mask:0xf
	v_pk_mul_f32 v[66:67], v[84:85], v[66:67]
	v_pk_mul_f32 v[62:63], v[62:63], v[104:105]
	v_pk_mul_f32 v[58:59], v[58:59], v[104:105]
	v_pk_mul_f32 v[104:105], v[74:75], v[200:201] op_sel_hi:[1,0]
	v_pk_mul_f32 v[74:75], v[64:65], v[200:201] op_sel_hi:[1,0]
	v_cndmask_b32_e64 v65, v123, v95, s[2:3]
	v_cndmask_b32_e64 v64, v121, v94, s[2:3]
	v_cndmask_b32_e64 v95, v129, v122, s[4:5]
	v_cndmask_b32_e64 v94, v128, v120, s[4:5]
	v_pk_fma_f32 v[66:67], v[80:81], v[96:97], v[66:67]
	v_pk_fma_f32 v[66:67], v[68:69], v[94:95], v[66:67]
	v_pk_add_f32 v[66:67], v[76:77], v[66:67]
	v_mov_b32_dpp v124, v104 row_ror:15 row_mask:0xf bank_mask:0xf
	v_mul_f32_e32 v94, v66, v66
	v_fmamk_f32 v94, v94, 0xbdd2d3e7, v232
	v_mul_f32_e32 v95, v67, v67
	v_mul_f32_e32 v94, v66, v94
	v_fmamk_f32 v95, v95, 0xbdd2d3e7, v232
	v_exp_f32_e32 v94, v94
	v_mul_f32_e32 v95, v67, v95
	v_exp_f32_e32 v95, v95
	v_mov_b32_dpp v125, v105 row_ror:15 row_mask:0xf bank_mask:0xf
	v_pk_mul_f32 v[64:65], v[86:87], v[64:65]
	v_cndmask_b32_e64 v93, v131, v125, s[4:5]
	v_cndmask_b32_e64 v92, v130, v124, s[4:5]
	v_pk_fma_f32 v[64:65], v[82:83], v[98:99], v[64:65]
	v_pk_fma_f32 v[64:65], v[70:71], v[92:93], v[64:65]
	v_add_f32_e32 v92, 1.0, v94
	v_rcp_f32_e32 v94, v92
	v_add_f32_e32 v92, 1.0, v95
	v_rcp_f32_e32 v95, v92
	v_pk_add_f32 v[92:93], v[78:79], v[64:65]
	v_mul_f32_e32 v64, v66, v94
	v_mul_f32_e32 v66, v92, v92
	v_mul_f32_e32 v65, v67, v95
	v_mul_f32_e32 v67, v93, v93
	v_fmamk_f32 v66, v66, 0xbdd2d3e7, v232
	v_fmamk_f32 v67, v67, 0xbdd2d3e7, v232
	v_mul_f32_e32 v66, v92, v66
	v_mul_f32_e32 v67, v93, v67
	v_exp_f32_e32 v66, v66
	v_exp_f32_e32 v67, v67
	v_mov_b32_dpp v108, v100 row_ror:1 row_mask:0xf bank_mask:0xf
	v_add_f32_e32 v66, 1.0, v66
	v_add_f32_e32 v67, 1.0, v67
	v_rcp_f32_e32 v66, v66
	v_rcp_f32_e32 v67, v67
	v_mov_b32_dpp v109, v101 row_ror:1 row_mask:0xf bank_mask:0xf
	v_pk_mul_f32 v[60:61], v[60:61], v[202:203]
	v_cndmask_b32_e64 v89, v109, v89, s[2:3]
	v_cndmask_b32_e64 v88, v108, v88, s[2:3]
	v_mov_b32_dpp v132, v100 row_ror:15 row_mask:0xf bank_mask:0xf
	v_mov_b32_dpp v133, v101 row_ror:15 row_mask:0xf bank_mask:0xf
	v_mov_b32_dpp v110, v74 row_ror:15 row_mask:0xf bank_mask:0xf
	v_mov_b32_dpp v114, v75 row_ror:15 row_mask:0xf bank_mask:0xf
	v_mul_f32_e32 v64, v60, v64
	v_mul_f32_e32 v65, v61, v65
	v_pk_mul_f32 v[88:89], v[44:45], v[88:89]
	v_cvt_pk_bf16_f32 v64, v64, v65
	v_mul_f32_e32 v65, v92, v66
	v_mul_f32_e32 v66, v93, v67
	v_cndmask_b32_e64 v93, v133, v114, s[4:5]
	v_cndmask_b32_e64 v92, v132, v110, s[4:5]
	v_pk_fma_f32 v[88:89], v[40:41], v[100:101], v[88:89]
	v_pk_fma_f32 v[88:89], v[32:33], v[92:93], v[88:89]
	v_pk_add_f32 v[88:89], v[36:37], v[88:89]
	v_mov_b32_dpp v111, v102 row_ror:1 row_mask:0xf bank_mask:0xf
	v_mul_f32_e32 v92, v88, v88
	v_fmamk_f32 v92, v92, 0xbdd2d3e7, v232
	v_mul_f32_e32 v93, v89, v89
	v_mul_f32_e32 v92, v88, v92
	v_fmamk_f32 v93, v93, 0xbdd2d3e7, v232
	v_mov_b32_dpp v115, v103 row_ror:1 row_mask:0xf bank_mask:0xf
	v_mul_f32_e32 v65, v62, v65
	v_mul_f32_e32 v66, v63, v66
	v_exp_f32_e32 v92, v92
	v_mul_f32_e32 v93, v89, v93
	v_cvt_pk_bf16_f32 v65, v65, v66
	v_cndmask_b32_e64 v67, v115, v91, s[2:3]
	v_cndmask_b32_e64 v66, v111, v90, s[2:3]
	v_exp_f32_e32 v93, v93
	v_mov_b32_dpp v134, v102 row_ror:15 row_mask:0xf bank_mask:0xf
	v_mov_b32_dpp v135, v103 row_ror:15 row_mask:0xf bank_mask:0xf
	v_mov_b32_dpp v116, v72 row_ror:15 row_mask:0xf bank_mask:0xf
	v_mov_b32_dpp v117, v73 row_ror:15 row_mask:0xf bank_mask:0xf
	v_pk_mul_f32 v[66:67], v[46:47], v[66:67]
	v_cndmask_b32_e64 v91, v135, v117, s[4:5]
	v_cndmask_b32_e64 v90, v134, v116, s[4:5]
	v_pk_fma_f32 v[66:67], v[42:43], v[102:103], v[66:67]
	v_pk_mul_f32 v[56:57], v[56:57], v[202:203]
	v_pk_fma_f32 v[66:67], v[34:35], v[90:91], v[66:67]
	v_add_f32_e32 v90, 1.0, v92
	v_rcp_f32_e32 v92, v90
	v_add_f32_e32 v90, 1.0, v93
	v_rcp_f32_e32 v93, v90
	v_pk_add_f32 v[90:91], v[38:39], v[66:67]
	v_mul_f32_e32 v66, v88, v92
	v_mul_f32_e32 v88, v90, v90
	v_mul_f32_e32 v67, v89, v93
	v_fmamk_f32 v88, v88, 0xbdd2d3e7, v232
	v_mul_f32_e32 v89, v91, v91
	v_mul_f32_e32 v88, v90, v88
	v_fmamk_f32 v89, v89, 0xbdd2d3e7, v232
	v_exp_f32_e32 v88, v88
	v_mul_f32_e32 v89, v91, v89
	v_exp_f32_e32 v89, v89
	v_add_u32_e32 v126, 0x80, v174
	v_add_f32_e32 v88, 1.0, v88
	v_rcp_f32_e32 v88, v88
	v_add_f32_e32 v89, 1.0, v89
	v_rcp_f32_e32 v89, v89
	v_mul_f32_e32 v66, v56, v66
	v_mul_f32_e32 v67, v57, v67
	v_and_b32_e32 v127, 0xcf, v126
	v_cvt_pk_bf16_f32 v66, v66, v67
	v_mul_f32_e32 v67, v90, v88
	v_mul_f32_e32 v67, v58, v67
	v_mul_f32_e32 v88, v91, v89
	v_cmp_eq_u32_e32 vcc, 0, v127
	v_cmp_ne_u32_e64 s[14:15], 0, v127
	v_mul_f32_e32 v88, v59, v88
	v_cvt_pk_bf16_f32 v67, v67, v88
	s_and_saveexec_b64 s[54:55], s[14:15]
	s_cbranch_execz .LBB0_1134
	v_readlane_b32 s14, v254, 15
	v_readlane_b32 s15, v254, 16
	s_nop 1
	v_mov_b64_e32 v[88:89], s[14:15]
	v_mad_i64_i32 v[88:89], s[14:15], v126, s75, v[88:89]
	v_lshl_add_u64 v[88:89], v[168:169], 1, v[88:89]
	global_store_dwordx4 v[88:89], v[64:67], off

; #define LAS __attribute__((address_space(3)))
;     __device__ __forceinline__ void operator()(f32x4 (&acc)[2][2][4][2], const Unit& u, int wr, int wc, int fr, int fq) const {
;     ...
;         for (int ai = 0; ai < 2; ++ai)
; #pragma unroll
;             for (int m = 0; m < 4; ++m) { const float rs = RS[wr * 64 + fr + ai * HALF + m * 16];
; #pragma unroll
;                 for (int bj = 0; bj < 2; ++bj)
; #pragma unroll
;                     for (int n = 0; n < 2; ++n) acc[ai][bj][m][n] *= rs; }
;         LAS float* XF = X; LAS float* XL = X + 4 * 128;
; #pragma unroll
;         for (int ai = 0; ai < 2; ++ai) { const int rb = 2 * ai + wr;
;             if (fr == 0) { *(LAS f32x4*)(XF + rb * 128 + cl) = acc[ai][0][0][0]; *(LAS f32x4*)(XF + rb * 128 + cl + 4) = acc[ai][0][0][1]; }
;             if (fr == 15) { *(LAS f32x4*)(XL + rb * 128 + cl) = acc[ai][0][3][0]; *(LAS f32x4*)(XL + rb * 128 + cl + 4) = acc[ai][0][3][1]; } }
;         asm volatile("s_waitcnt lgkmcnt(0)" ::: "memory"); __builtin_amdgcn_s_barrier(); asm volatile("" ::: "memory");
; #pragma unroll
;         for (int ai = 0; ai < 2; ++ai) {
;             const int rb = 2 * ai + wr;
;             f32x4 Sprev[2], Scur[2], Tcur[2], Tnext[2];
; #pragma unroll
;             for (int n = 0; n < 2; ++n) { Sprev[n] = (rb > 0) ? *(const LAS f32x4*)(XL + (rb - 1) * 128 + cl + 4 * n) : (f32x4){0.f, 0.f, 0.f, 0.f};
; #pragma unroll
;                 for (int j = 0; j < 4; ++j) Tcur[n][j] = dpp_rol1(acc[ai][0][0][n][j]); }
; #pragma unroll
;             for (int m = 0; m < 4; ++m) {
; #pragma unroll
;                 for (int n = 0; n < 2; ++n) {
; #pragma unroll
;                     for (int j = 0; j < 4; ++j) Scur[n][j] = dpp_ror1(acc[ai][0][m][n][j]);
;                     if (m < 3) {
; #pragma unroll
;                         for (int j = 0; j < 4; ++j) Tnext[n][j] = dpp_rol1(acc[ai][0][m < 3 ? m + 1 : 3][n][j]);
;                     } else Tnext[n] = (rb < 3) ? *(const LAS f32x4*)(XF + (rb + 1) * 128 + cl + 4 * n) : (f32x4){0.f, 0.f, 0.f, 0.f};
;                 }
;                 const int row = row0 + ai * HALF + m * 16, lrow = row & 255;
;                 const bool edge = (lrow == 0) || (lrow == 255);
;                 u32x4 ow;
; #pragma unroll
;                 for (int n = 0; n < 2; ++n) {
;                     const f32x4 up = (fr == 0) ? Sprev[n] : Scur[n], dn = (fr == 15) ? Tnext[n] : Tcur[n];
.LBB0_1137:
	s_or_b64 exec, exec, s[54:55]
	v_mov_b32_e32 v201, v200
	v_mov_b32_e32 v56, v200
	v_mov_b32_e32 v57, v200
	v_mov_b32_dpp v88, v106 row_ror:1 row_mask:0xf bank_mask:0xf
	v_mov_b32_dpp v89, v107 row_ror:1 row_mask:0xf bank_mask:0xf
	v_pk_mul_f32 v[58:59], v[22:23], v[56:57]
	v_pk_mul_f32 v[62:63], v[16:17], v[200:201]
	v_pk_mul_f32 v[22:23], v[28:29], v[198:199] op_sel_hi:[1,0]
	v_pk_mul_f32 v[16:17], v[26:27], v[198:199] op_sel_hi:[1,0]
	v_cndmask_b32_e64 v27, v89, v119, s[2:3]
	v_cndmask_b32_e64 v26, v88, v118, s[2:3]
	v_mov_b32_dpp v90, v22 row_ror:15 row_mask:0xf bank_mask:0xf
	v_mov_b32_dpp v91, v23 row_ror:15 row_mask:0xf bank_mask:0xf
	v_pk_mul_f32 v[26:27], v[84:85], v[26:27]
	v_pk_mul_f32 v[60:61], v[20:21], v[200:201]
	v_pk_mul_f32 v[20:21], v[30:31], v[198:199] op_sel_hi:[1,0]
	v_cndmask_b32_e64 v31, v122, v91, s[4:5]
	v_cndmask_b32_e64 v30, v120, v90, s[4:5]
	v_pk_fma_f32 v[26:27], v[80:81], v[106:107], v[26:27]
	v_pk_fma_f32 v[26:27], v[68:69], v[30:31], v[26:27]
	v_pk_add_f32 v[26:27], v[76:77], v[26:27]
	v_mov_b32_dpp v66, v104 row_ror:1 row_mask:0xf bank_mask:0xf
	v_mul_f32_e32 v30, v26, v26
	v_fmamk_f32 v30, v30, 0xbdd2d3e7, v232
	v_mul_f32_e32 v31, v27, v27
	v_mul_f32_e32 v30, v26, v30
	v_fmamk_f32 v31, v31, 0xbdd2d3e7, v232
	v_mov_b32_dpp v67, v105 row_ror:1 row_mask:0xf bank_mask:0xf
	v_exp_f32_e32 v30, v30
	v_mul_f32_e32 v31, v27, v31
	v_pk_mul_f32 v[56:57], v[18:19], v[56:57]
	v_pk_mul_f32 v[18:19], v[24:25], v[198:199] op_sel_hi:[1,0]
	v_cndmask_b32_e64 v25, v67, v123, s[2:3]
	v_cndmask_b32_e64 v24, v66, v121, s[2:3]
	v_exp_f32_e32 v31, v31
	v_mov_b32_dpp v92, v20 row_ror:15 row_mask:0xf bank_mask:0xf
	v_mov_b32_dpp v93, v21 row_ror:15 row_mask:0xf bank_mask:0xf
	v_pk_mul_f32 v[24:25], v[86:87], v[24:25]
	v_cndmask_b32_e64 v29, v125, v93, s[4:5]
	v_cndmask_b32_e64 v28, v124, v92, s[4:5]
	v_pk_fma_f32 v[24:25], v[82:83], v[104:105], v[24:25]
	v_pk_fma_f32 v[24:25], v[70:71], v[28:29], v[24:25]
	v_add_f32_e32 v28, 1.0, v30
	v_rcp_f32_e32 v30, v28
	v_add_f32_e32 v28, 1.0, v31
	v_rcp_f32_e32 v31, v28
	v_pk_add_f32 v[28:29], v[78:79], v[24:25]
	v_mul_f32_e32 v24, v26, v30
	v_mul_f32_e32 v26, v28, v28
	v_mul_f32_e32 v25, v27, v31
	v_mul_f32_e32 v27, v29, v29
	v_fmamk_f32 v26, v26, 0xbdd2d3e7, v232
	v_fmamk_f32 v27, v27, 0xbdd2d3e7, v232
	v_mul_f32_e32 v26, v28, v26
	v_mul_f32_e32 v27, v29, v27
	v_exp_f32_e32 v26, v26
	v_exp_f32_e32 v27, v27
	v_mov_b32_dpp v94, v74 row_ror:1 row_mask:0xf bank_mask:0xf
	v_add_f32_e32 v26, 1.0, v26
	v_add_f32_e32 v27, 1.0, v27
	v_rcp_f32_e32 v26, v26
	v_rcp_f32_e32 v27, v27
	v_mov_b32_dpp v95, v75 row_ror:1 row_mask:0xf bank_mask:0xf
	v_mul_f32_e32 v24, v60, v24
	v_mul_f32_e32 v25, v61, v25
	v_cvt_pk_bf16_f32 v24, v24, v25
	v_mul_f32_e32 v25, v28, v26
	v_mul_f32_e32 v26, v29, v27
	v_cndmask_b32_e64 v29, v95, v109, s[2:3]
	v_cndmask_b32_e64 v28, v94, v108, s[2:3]
	v_mov_b32_dpp v98, v18 row_ror:15 row_mask:0xf bank_mask:0xf
	v_mov_b32_dpp v99, v19 row_ror:15 row_mask:0xf bank_mask:0xf
	v_pk_mul_f32 v[28:29], v[44:45], v[28:29]
	v_mul_f32_e32 v25, v58, v25
	v_mul_f32_e32 v26, v59, v26
	v_cndmask_b32_e64 v59, v114, v99, s[4:5]
	v_cndmask_b32_e64 v58, v110, v98, s[4:5]
	v_pk_fma_f32 v[28:29], v[40:41], v[74:75], v[28:29]
	v_pk_fma_f32 v[28:29], v[32:33], v[58:59], v[28:29]
	v_pk_add_f32 v[28:29], v[36:37], v[28:29]
	v_mov_b32_dpp v96, v72 row_ror:1 row_mask:0xf bank_mask:0xf
	v_mul_f32_e32 v58, v28, v28
	v_fmamk_f32 v58, v58, 0xbdd2d3e7, v232
	v_mul_f32_e32 v59, v29, v29
	v_mul_f32_e32 v58, v28, v58
	v_fmamk_f32 v59, v59, 0xbdd2d3e7, v232
	v_mov_b32_dpp v97, v73 row_ror:1 row_mask:0xf bank_mask:0xf
	v_exp_f32_e32 v58, v58
	v_mul_f32_e32 v59, v29, v59
	v_cvt_pk_bf16_f32 v25, v25, v26
	v_cndmask_b32_e64 v27, v97, v115, s[2:3]
	v_cndmask_b32_e64 v26, v96, v111, s[2:3]
	v_exp_f32_e32 v59, v59
	v_mov_b32_dpp v100, v16 row_ror:15 row_mask:0xf bank_mask:0xf
	v_mov_b32_dpp v101, v17 row_ror:15 row_mask:0xf bank_mask:0xf
	v_pk_mul_f32 v[26:27], v[46:47], v[26:27]
	v_cndmask_b32_e64 v31, v117, v101, s[4:5]
	v_cndmask_b32_e64 v30, v116, v100, s[4:5]
	v_pk_fma_f32 v[26:27], v[42:43], v[72:73], v[26:27]
	v_pk_fma_f32 v[26:27], v[34:35], v[30:31], v[26:27]
	v_add_f32_e32 v30, 1.0, v58
	v_rcp_f32_e32 v58, v30
	v_add_f32_e32 v30, 1.0, v59
	v_rcp_f32_e32 v59, v30
	v_pk_add_f32 v[30:31], v[38:39], v[26:27]
	v_mul_f32_e32 v26, v28, v58
	v_mul_f32_e32 v28, v30, v30
	v_mul_f32_e32 v27, v29, v59
	v_mul_f32_e32 v29, v31, v31
	v_fmamk_f32 v28, v28, 0xbdd2d3e7, v232
	v_fmamk_f32 v29, v29, 0xbdd2d3e7, v232
	v_mul_f32_e32 v28, v30, v28
	v_mul_f32_e32 v29, v31, v29
	v_exp_f32_e32 v28, v28
	v_exp_f32_e32 v29, v29
	v_mul_f32_e32 v26, v62, v26
	v_mul_f32_e32 v27, v63, v27
	v_add_f32_e32 v28, 1.0, v28
	v_add_f32_e32 v29, 1.0, v29
	v_rcp_f32_e32 v28, v28
	v_rcp_f32_e32 v29, v29
	v_cvt_pk_bf16_f32 v26, v26, v27
	v_mul_f32_e32 v27, v30, v28
	v_mul_f32_e32 v28, v31, v29
	v_mul_f32_e32 v27, v56, v27
	v_mul_f32_e32 v28, v57, v28
	v_mov_b32_dpp v56, v22 row_ror:1 row_mask:0xf bank_mask:0xf
	v_mov_b32_dpp v57, v23 row_ror:1 row_mask:0xf bank_mask:0xf
	v_cndmask_b32_e64 v73, v57, v89, s[2:3]
	v_cndmask_b32_e64 v72, v56, v88, s[2:3]
	v_mov_b32_dpp v58, v48 row_ror:15 row_mask:0xf bank_mask:0xf
	v_mov_b32_dpp v60, v49 row_ror:15 row_mask:0xf bank_mask:0xf
	v_pk_mul_f32 v[72:73], v[84:85], v[72:73]
	v_mov_b32_dpp v59, v20 row_ror:1 row_mask:0xf bank_mask:0xf
	v_mov_b32_dpp v61, v21 row_ror:1 row_mask:0xf bank_mask:0xf
	v_cndmask_b32_e64 v89, v91, v60, s[4:5]
	v_cndmask_b32_e64 v88, v90, v58, s[4:5]
; #define LAS __attribute__((address_space(3)))
;     __device__ __forceinline__ void operator()(f32x4 (&acc)[2][2][4][2], const Unit& u, int wr, int wc, int fr, int fq) const {
;     ...
;         for (int ai = 0; ai < 2; ++ai)
; #pragma unroll
;             for (int m = 0; m < 4; ++m) { const float rs = RS[wr * 64 + fr + ai * HALF + m * 16];
; #pragma unroll
;                 for (int bj = 0; bj < 2; ++bj)
; #pragma unroll
;                     for (int n = 0; n < 2; ++n) acc[ai][bj][m][n] *= rs; }
;         LAS float* XF = X; LAS float* XL = X + 4 * 128;
; #pragma unroll
;         for (int ai = 0; ai < 2; ++ai) { const int rb = 2 * ai + wr;
;             if (fr == 0) { *(LAS f32x4*)(XF + rb * 128 + cl) = acc[ai][0][0][0]; *(LAS f32x4*)(XF + rb * 128 + cl + 4) = acc[ai][0][0][1]; }
;             if (fr == 15) { *(LAS f32x4*)(XL + rb * 128 + cl) = acc[ai][0][3][0]; *(LAS f32x4*)(XL + rb * 128 + cl + 4) = acc[ai][0][3][1]; } }
;         asm volatile("s_waitcnt lgkmcnt(0)" ::: "memory"); __builtin_amdgcn_s_barrier(); asm volatile("" ::: "memory");
; #pragma unroll
;         for (int ai = 0; ai < 2; ++ai) {
;             const int rb = 2 * ai + wr;
;             f32x4 Sprev[2], Scur[2], Tcur[2], Tnext[2];
; #pragma unroll
;             for (int n = 0; n < 2; ++n) { Sprev[n] = (rb > 0) ? *(const LAS f32x4*)(XL + (rb - 1) * 128 + cl + 4 * n) : (f32x4){0.f, 0.f, 0.f, 0.f};
; #pragma unroll
;                 for (int j = 0; j < 4; ++j) Tcur[n][j] = dpp_rol1(acc[ai][0][0][n][j]); }
; #pragma unroll
;             for (int m = 0; m < 4; ++m) {
; #pragma unroll
;                 for (int n = 0; n < 2; ++n) {
; #pragma unroll
;                     for (int j = 0; j < 4; ++j) Scur[n][j] = dpp_ror1(acc[ai][0][m][n][j]);
;                     if (m < 3) {
; #pragma unroll
;                         for (int j = 0; j < 4; ++j) Tnext[n][j] = dpp_rol1(acc[ai][0][m < 3 ? m + 1 : 3][n][j]);
;                     } else Tnext[n] = (rb < 3) ? *(const LAS f32x4*)(XF + (rb + 1) * 128 + cl + 4 * n) : (f32x4){0.f, 0.f, 0.f, 0.f};
;                 }
;                 const int row = row0 + ai * HALF + m * 16, lrow = row & 255;
;                 const bool edge = (lrow == 0) || (lrow == 255);
;                 u32x4 ow;
; #pragma unroll
;                 for (int n = 0; n < 2; ++n) {
;                     const f32x4 up = (fr == 0) ? Sprev[n] : Scur[n], dn = (fr == 15) ? Tnext[n] : Tcur[n];
	v_pk_fma_f32 v[22:23], v[80:81], v[22:23], v[72:73]
	v_cndmask_b32_e64 v67, v61, v67, s[2:3]
	v_cndmask_b32_e64 v66, v59, v66, s[2:3]
	v_pk_fma_f32 v[22:23], v[68:69], v[88:89], v[22:23]
	v_pk_mul_f32 v[66:67], v[86:87], v[66:67]
	v_pk_add_f32 v[22:23], v[76:77], v[22:23]
	v_pk_fma_f32 v[20:21], v[82:83], v[20:21], v[66:67]
	v_mul_f32_e32 v66, v22, v22
	v_fmamk_f32 v66, v66, 0xbdd2d3e7, v232
	v_mul_f32_e32 v67, v23, v23
	v_mul_f32_e32 v66, v22, v66
	v_fmamk_f32 v67, v67, 0xbdd2d3e7, v232
	v_exp_f32_e32 v66, v66
	v_mul_f32_e32 v67, v23, v67
	v_exp_f32_e32 v67, v67
	v_add_f32_e32 v66, 1.0, v66
	v_rcp_f32_e32 v66, v66
	v_add_f32_e32 v67, 1.0, v67
	v_mov_b32_dpp v62, v50 row_ror:15 row_mask:0xf bank_mask:0xf
	v_mov_b32_dpp v63, v51 row_ror:15 row_mask:0xf bank_mask:0xf
	v_rcp_f32_e32 v67, v67
	v_cndmask_b32_e64 v75, v93, v63, s[4:5]
	v_cndmask_b32_e64 v74, v92, v62, s[4:5]
	v_pk_fma_f32 v[20:21], v[70:71], v[74:75], v[20:21]
	v_pk_mul_f32 v[12:13], v[12:13], v[198:199] op_sel_hi:[1,0]
	v_pk_add_f32 v[20:21], v[78:79], v[20:21]
	v_mul_f32_e32 v22, v22, v66
	v_mul_f32_e32 v12, v12, v22
	v_mul_f32_e32 v22, v23, v67
	v_mul_f32_e32 v23, v20, v20
	v_fmamk_f32 v23, v23, 0xbdd2d3e7, v232
	v_mul_f32_e32 v66, v21, v21
	v_mul_f32_e32 v23, v20, v23
	v_fmamk_f32 v66, v66, 0xbdd2d3e7, v232
	v_exp_f32_e32 v23, v23
	v_mul_f32_e32 v66, v21, v66
	v_exp_f32_e32 v66, v66
	v_readlane_b32 s14, v254, 15
	v_mul_f32_e32 v13, v13, v22
	v_add_f32_e32 v22, 1.0, v23
	v_readlane_b32 s15, v254, 16
	v_rcp_f32_e32 v22, v22
	v_add_f32_e32 v23, 1.0, v66
	v_add_u32_e32 v102, 0x90, v174
	v_mov_b64_e32 v[64:65], s[14:15]
	v_rcp_f32_e32 v23, v23
	v_cvt_pk_bf16_f32 v27, v27, v28
	v_mad_i64_i32 v[28:29], s[14:15], v102, s75, v[64:65]
	v_lshl_add_u64 v[28:29], v[28:29], 0, v[112:113]
	v_pk_mul_f32 v[14:15], v[14:15], v[198:199] op_sel_hi:[1,0]
	global_store_dwordx4 v[28:29], v[24:27], off
	v_cvt_pk_bf16_f32 v12, v12, v13
	v_mul_f32_e32 v13, v20, v22
	v_mul_f32_e32 v13, v14, v13
	v_mul_f32_e32 v14, v21, v23
	v_mov_b32_dpp v24, v18 row_ror:1 row_mask:0xf bank_mask:0xf
	v_mov_b32_dpp v25, v19 row_ror:1 row_mask:0xf bank_mask:0xf
	v_mov_b32_dpp v27, v16 row_ror:1 row_mask:0xf bank_mask:0xf
	v_mov_b32_dpp v29, v17 row_ror:1 row_mask:0xf bank_mask:0xf
	v_mul_f32_e32 v14, v15, v14
	v_cvt_pk_bf16_f32 v13, v13, v14
	v_cndmask_b32_e64 v15, v29, v97, s[2:3]
	v_cndmask_b32_e64 v14, v27, v96, s[2:3]
	v_cndmask_b32_e64 v21, v25, v95, s[2:3]
	v_cndmask_b32_e64 v20, v24, v94, s[2:3]
	v_mov_b32_dpp v26, v52 row_ror:15 row_mask:0xf bank_mask:0xf
	v_mov_b32_dpp v28, v53 row_ror:15 row_mask:0xf bank_mask:0xf
	v_pk_mul_f32 v[20:21], v[44:45], v[20:21]
	v_pk_mul_f32 v[14:15], v[46:47], v[14:15]
	v_cndmask_b32_e64 v67, v99, v28, s[4:5]
	v_cndmask_b32_e64 v66, v98, v26, s[4:5]
	v_pk_fma_f32 v[14:15], v[42:43], v[16:17], v[14:15]
	v_pk_fma_f32 v[16:17], v[40:41], v[18:19], v[20:21]
	v_pk_fma_f32 v[16:17], v[32:33], v[66:67], v[16:17]
	v_pk_add_f32 v[16:17], v[36:37], v[16:17]
	v_mov_b32_dpp v30, v54 row_ror:15 row_mask:0xf bank_mask:0xf
	v_mul_f32_e32 v18, v16, v16
	v_fmamk_f32 v18, v18, 0xbdd2d3e7, v232
	v_mul_f32_e32 v18, v16, v18
	v_mul_f32_e32 v19, v17, v17
	v_exp_f32_e32 v18, v18
	v_fmamk_f32 v19, v19, 0xbdd2d3e7, v232
	v_mul_f32_e32 v19, v17, v19
	v_exp_f32_e32 v19, v19
	v_mov_b32_dpp v31, v55 row_ror:15 row_mask:0xf bank_mask:0xf
	v_add_f32_e32 v18, 1.0, v18
	v_cndmask_b32_e64 v23, v101, v31, s[4:5]
	v_cndmask_b32_e64 v22, v100, v30, s[4:5]
	v_rcp_f32_e32 v20, v18
	v_pk_fma_f32 v[14:15], v[34:35], v[22:23], v[14:15]
	v_add_f32_e32 v18, 1.0, v19
	v_rcp_f32_e32 v21, v18
	v_pk_add_f32 v[18:19], v[38:39], v[14:15]
	v_mul_f32_e32 v14, v16, v20
	v_mul_f32_e32 v15, v18, v18
	v_fmamk_f32 v15, v15, 0xbdd2d3e7, v232
	v_mul_f32_e32 v16, v19, v19
	v_mul_f32_e32 v15, v18, v15
	v_fmamk_f32 v16, v16, 0xbdd2d3e7, v232
	v_exp_f32_e32 v15, v15
	v_mul_f32_e32 v16, v19, v16
	v_exp_f32_e32 v16, v16
	v_pk_mul_f32 v[8:9], v[8:9], v[198:199] op_sel_hi:[1,0]
	v_pk_mul_f32 v[10:11], v[10:11], v[198:199] op_sel_hi:[1,0]
	v_mul_f32_e32 v8, v8, v14
	v_mul_f32_e32 v14, v17, v21
	v_mul_f32_e32 v9, v9, v14
	v_add_f32_e32 v14, 1.0, v15
	v_rcp_f32_e32 v15, v14
	v_add_f32_e32 v14, 1.0, v16
	v_rcp_f32_e32 v16, v14
	v_cvt_pk_bf16_f32 v14, v8, v9
	v_mul_f32_e32 v8, v18, v15
	v_add_u32_e32 v102, 0xa0, v174
	v_mul_f32_e32 v9, v19, v16
	v_mul_f32_e32 v8, v10, v8
	v_mul_f32_e32 v9, v11, v9
	v_cvt_pk_bf16_f32 v15, v8, v9
	v_mad_i64_i32 v[8:9], s[14:15], v102, s75, v[64:65]
	v_lshl_add_u64 v[8:9], v[8:9], 0, v[112:113]
	global_store_dwordx4 v[8:9], v[12:15], off
	v_cndmask_b32_e64 v9, 0, 1, s[40:41]
	v_mov_b32_dpp v21, v48 row_ror:1 row_mask:0xf bank_mask:0xf
	v_mov_b32_dpp v22, v49 row_ror:1 row_mask:0xf bank_mask:0xf
	v_mov_b32_dpp v23, v50 row_ror:1 row_mask:0xf bank_mask:0xf
	v_mov_b32_dpp v64, v51 row_ror:1 row_mask:0xf bank_mask:0xf
	v_mov_b32_e32 v8, 0
	v_cmp_ne_u32_e64 s[14:15], 1, v9
	s_andn2_b64 vcc, exec, s[40:41]
	v_mov_b32_e32 v12, 0
	v_mov_b32_e32 v13, 0
	v_mov_b32_e32 v14, 0
	v_mov_b32_e32 v15, 0
	s_cbranch_vccnz .LBB0_1139
	ds_read_b128 v[12:15], v227 offset:512
.LBB0_1139:
	v_mov_b32_dpp v17, v52 row_ror:1 row_mask:0xf bank_mask:0xf
	v_mov_b32_dpp v18, v53 row_ror:1 row_mask:0xf bank_mask:0xf
	v_mov_b32_dpp v19, v54 row_ror:1 row_mask:0xf bank_mask:0xf
	v_mov_b32_dpp v20, v55 row_ror:1 row_mask:0xf bank_mask:0xf
	s_and_b64 vcc, exec, s[14:15]
	v_mov_b32_e32 v9, 0
	v_mov_b32_e32 v10, 0
	v_mov_b32_e32 v11, 0
	s_cbranch_vccnz .LBB0_1141
	ds_read_b128 v[8:11], v227 offset:528

; #define LAS __attribute__((address_space(3)))
;     __device__ __forceinline__ void operator()(f32x4 (&acc)[2][2][4][2], const Unit& u, int wr, int wc, int fr, int fq) const {
;     ...
;         for (int ai = 0; ai < 2; ++ai)
; #pragma unroll
;             for (int m = 0; m < 4; ++m) { const float rs = RS[wr * 64 + fr + ai * HALF + m * 16];
; #pragma unroll
;                 for (int bj = 0; bj < 2; ++bj)
; #pragma unroll
;                     for (int n = 0; n < 2; ++n) acc[ai][bj][m][n] *= rs; }
;         LAS float* XF = X; LAS float* XL = X + 4 * 128;
; #pragma unroll
;         for (int ai = 0; ai < 2; ++ai) { const int rb = 2 * ai + wr;
;             if (fr == 0) { *(LAS f32x4*)(XF + rb * 128 + cl) = acc[ai][0][0][0]; *(LAS f32x4*)(XF + rb * 128 + cl + 4) = acc[ai][0][0][1]; }
;             if (fr == 15) { *(LAS f32x4*)(XL + rb * 128 + cl) = acc[ai][0][3][0]; *(LAS f32x4*)(XL + rb * 128 + cl + 4) = acc[ai][0][3][1]; } }
;         asm volatile("s_waitcnt lgkmcnt(0)" ::: "memory"); __builtin_amdgcn_s_barrier(); asm volatile("" ::: "memory");
; #pragma unroll
;         for (int ai = 0; ai < 2; ++ai) {
;             const int rb = 2 * ai + wr;
;             f32x4 Sprev[2], Scur[2], Tcur[2], Tnext[2];
; #pragma unroll
;             for (int n = 0; n < 2; ++n) { Sprev[n] = (rb > 0) ? *(const LAS f32x4*)(XL + (rb - 1) * 128 + cl + 4 * n) : (f32x4){0.f, 0.f, 0.f, 0.f};
; #pragma unroll
;                 for (int j = 0; j < 4; ++j) Tcur[n][j] = dpp_rol1(acc[ai][0][0][n][j]); }
; #pragma unroll
;             for (int m = 0; m < 4; ++m) {
; #pragma unroll
;                 for (int n = 0; n < 2; ++n) {
; #pragma unroll
;                     for (int j = 0; j < 4; ++j) Scur[n][j] = dpp_ror1(acc[ai][0][m][n][j]);
;                     if (m < 3) {
; #pragma unroll
;                         for (int j = 0; j < 4; ++j) Tnext[n][j] = dpp_rol1(acc[ai][0][m < 3 ? m + 1 : 3][n][j]);
;                     } else Tnext[n] = (rb < 3) ? *(const LAS f32x4*)(XF + (rb + 1) * 128 + cl + 4 * n) : (f32x4){0.f, 0.f, 0.f, 0.f};
;                 }
;                 const int row = row0 + ai * HALF + m * 16, lrow = row & 255;
;                 const bool edge = (lrow == 0) || (lrow == 255);
;                 u32x4 ow;
; #pragma unroll
;                 for (int n = 0; n < 2; ++n) {
;                     const f32x4 up = (fr == 0) ? Sprev[n] : Scur[n], dn = (fr == 15) ? Tnext[n] : Tcur[n];
.LBB0_2051:
	v_pk_mul_f32 v[172:173], v[148:149], v[208:209] op_sel_hi:[1,0]
	v_mov_b32_dpp v236, v160 row_ror:1 row_mask:0xf bank_mask:0xf
	v_mov_b32_dpp v237, v161 row_ror:1 row_mask:0xf bank_mask:0xf
	v_pk_mul_f32 v[148:149], v[146:147], v[208:209] op_sel_hi:[1,0]
	s_waitcnt lgkmcnt(0)
	v_cndmask_b32_e64 v147, v237, v157, s[2:3]
	v_cndmask_b32_e64 v146, v236, v156, s[2:3]
	v_mov_b32_e32 v170, v210
	v_mov_b32_e32 v171, v210
	v_mov_b32_dpp v239, v162 row_ror:1 row_mask:0xf bank_mask:0xf
	v_mov_b32_dpp v241, v163 row_ror:1 row_mask:0xf bank_mask:0xf
	v_mov_b32_dpp v238, v172 row_ror:15 row_mask:0xf bank_mask:0xf
	v_mov_b32_dpp v240, v173 row_ror:15 row_mask:0xf bank_mask:0xf
	v_pk_mul_f32 v[146:147], v[84:85], v[146:147]
	v_pk_mul_f32 v[142:143], v[142:143], v[170:171]
	v_pk_mul_f32 v[138:139], v[138:139], v[170:171]
	v_pk_mul_f32 v[170:171], v[150:151], v[208:209] op_sel_hi:[1,0]
	v_pk_mul_f32 v[150:151], v[144:145], v[208:209] op_sel_hi:[1,0]
	v_cndmask_b32_e64 v145, v241, v159, s[2:3]
	v_cndmask_b32_e64 v144, v239, v158, s[2:3]
	v_cndmask_b32_e64 v159, v244, v240, s[4:5]
	v_cndmask_b32_e64 v158, v209, v238, s[4:5]
	v_pk_fma_f32 v[146:147], v[80:81], v[160:161], v[146:147]
	v_pk_fma_f32 v[146:147], v[68:69], v[158:159], v[146:147]
	v_pk_add_f32 v[146:147], v[76:77], v[146:147]
	v_mov_b32_dpp v242, v170 row_ror:15 row_mask:0xf bank_mask:0xf
	v_mul_f32_e32 v158, v146, v146
	v_fmamk_f32 v158, v158, 0xbdd2d3e7, v232
	v_mul_f32_e32 v159, v147, v147
	v_mul_f32_e32 v158, v146, v158
	v_fmamk_f32 v159, v159, 0xbdd2d3e7, v232
	v_exp_f32_e32 v158, v158
	v_mul_f32_e32 v159, v147, v159
	v_exp_f32_e32 v159, v159
	v_mov_b32_dpp v243, v171 row_ror:15 row_mask:0xf bank_mask:0xf
	v_pk_mul_f32 v[144:145], v[86:87], v[144:145]
	v_cndmask_b32_e64 v157, v246, v243, s[4:5]
	v_cndmask_b32_e64 v156, v245, v242, s[4:5]
	v_pk_fma_f32 v[144:145], v[82:83], v[162:163], v[144:145]
	v_pk_fma_f32 v[144:145], v[70:71], v[156:157], v[144:145]
	v_add_f32_e32 v156, 1.0, v158
	v_rcp_f32_e32 v158, v156
	v_add_f32_e32 v156, 1.0, v159
	v_rcp_f32_e32 v159, v156
	v_pk_add_f32 v[156:157], v[78:79], v[144:145]
	v_mul_f32_e32 v144, v146, v158
	v_mul_f32_e32 v146, v156, v156
	v_mul_f32_e32 v145, v147, v159
	v_mul_f32_e32 v147, v157, v157
	v_fmamk_f32 v146, v146, 0xbdd2d3e7, v232
	v_fmamk_f32 v147, v147, 0xbdd2d3e7, v232
	v_mul_f32_e32 v146, v156, v146
	v_mul_f32_e32 v147, v157, v147
	v_exp_f32_e32 v146, v146
	v_exp_f32_e32 v147, v147
	v_mov_b32_dpp v175, v164 row_ror:1 row_mask:0xf bank_mask:0xf
	v_add_f32_e32 v146, 1.0, v146
	v_add_f32_e32 v147, 1.0, v147
	v_rcp_f32_e32 v146, v146
	v_rcp_f32_e32 v147, v147
	v_mov_b32_dpp v199, v165 row_ror:1 row_mask:0xf bank_mask:0xf
	v_pk_mul_f32 v[140:141], v[140:141], v[210:211]
	v_pk_mul_f32 v[136:137], v[136:137], v[210:211]
	v_cndmask_b32_e64 v153, v199, v153, s[2:3]
	v_cndmask_b32_e64 v152, v175, v152, s[2:3]
	v_mov_b32_dpp v247, v164 row_ror:15 row_mask:0xf bank_mask:0xf
	v_mov_b32_dpp v248, v165 row_ror:15 row_mask:0xf bank_mask:0xf
	v_mov_b32_dpp v201, v150 row_ror:15 row_mask:0xf bank_mask:0xf
	v_mov_b32_dpp v210, v151 row_ror:15 row_mask:0xf bank_mask:0xf
	v_mul_f32_e32 v144, v140, v144
	v_mul_f32_e32 v145, v141, v145
	v_pk_mul_f32 v[152:153], v[44:45], v[152:153]
	v_cvt_pk_bf16_f32 v144, v144, v145
	v_mul_f32_e32 v145, v156, v146
	v_mul_f32_e32 v146, v157, v147
	v_cndmask_b32_e64 v157, v248, v210, s[4:5]
	v_cndmask_b32_e64 v156, v247, v201, s[4:5]
	v_pk_fma_f32 v[152:153], v[40:41], v[164:165], v[152:153]
	v_pk_fma_f32 v[152:153], v[32:33], v[156:157], v[152:153]
	v_pk_add_f32 v[152:153], v[36:37], v[152:153]
	v_mov_b32_dpp v207, v166 row_ror:1 row_mask:0xf bank_mask:0xf
	v_mul_f32_e32 v156, v152, v152
	v_fmamk_f32 v156, v156, 0xbdd2d3e7, v232
	v_mul_f32_e32 v157, v153, v153
	v_mul_f32_e32 v156, v152, v156
	v_fmamk_f32 v157, v157, 0xbdd2d3e7, v232
	v_mov_b32_dpp v211, v167 row_ror:1 row_mask:0xf bank_mask:0xf
	v_mul_f32_e32 v145, v142, v145
	v_mul_f32_e32 v146, v143, v146
	v_exp_f32_e32 v156, v156
	v_mul_f32_e32 v157, v153, v157
	v_cvt_pk_bf16_f32 v145, v145, v146
	v_cndmask_b32_e64 v147, v211, v155, s[2:3]
	v_cndmask_b32_e64 v146, v207, v154, s[2:3]
	v_exp_f32_e32 v157, v157
	v_mov_b32_dpp v249, v166 row_ror:15 row_mask:0xf bank_mask:0xf
	v_mov_b32_dpp v250, v167 row_ror:15 row_mask:0xf bank_mask:0xf
	v_mov_b32_dpp v234, v148 row_ror:15 row_mask:0xf bank_mask:0xf
	v_mov_b32_dpp v235, v149 row_ror:15 row_mask:0xf bank_mask:0xf
	v_pk_mul_f32 v[146:147], v[46:47], v[146:147]
	v_cndmask_b32_e64 v155, v250, v235, s[4:5]
	v_cndmask_b32_e64 v154, v249, v234, s[4:5]
	v_pk_fma_f32 v[146:147], v[42:43], v[166:167], v[146:147]
	v_or_b32_e32 v168, s50, v214
	v_pk_fma_f32 v[146:147], v[34:35], v[154:155], v[146:147]
	v_add_f32_e32 v154, 1.0, v156
	v_rcp_f32_e32 v156, v154
	v_add_f32_e32 v154, 1.0, v157
	v_rcp_f32_e32 v157, v154
	v_pk_add_f32 v[154:155], v[38:39], v[146:147]
	v_mul_f32_e32 v146, v152, v156
	v_mul_f32_e32 v152, v154, v154
	v_mul_f32_e32 v147, v153, v157
	v_fmamk_f32 v152, v152, 0xbdd2d3e7, v232
	v_mul_f32_e32 v153, v155, v155
	v_mul_f32_e32 v152, v154, v152
	v_fmamk_f32 v153, v153, 0xbdd2d3e7, v232
	v_exp_f32_e32 v152, v152
	v_mul_f32_e32 v153, v155, v153
	v_exp_f32_e32 v153, v153
	v_mul_f32_e32 v146, v136, v146
	v_add_f32_e32 v152, 1.0, v152
	v_rcp_f32_e32 v152, v152
	v_add_f32_e32 v153, 1.0, v153
	v_rcp_f32_e32 v153, v153
	v_mul_f32_e32 v147, v137, v147
	v_cvt_pk_bf16_f32 v146, v146, v147
	v_mul_f32_e32 v147, v154, v152
	v_ashrrev_i32_e32 v169, 31, v168
	v_add_u32_e32 v174, s19, v212
	v_mul_f32_e32 v147, v138, v147
	v_mul_f32_e32 v152, v155, v153
	v_mul_f32_e32 v152, v139, v152
	v_cvt_pk_bf16_f32 v147, v147, v152
	s_and_saveexec_b64 s[14:15], s[8:9]
	s_cbranch_execz .LBB0_2053
	v_readlane_b32 s50, v254, 15
	v_readlane_b32 s51, v254, 16
	s_nop 1
	v_mov_b64_e32 v[152:153], s[50:51]
	v_mad_i64_i32 v[152:153], s[50:51], v174, s73, v[152:153]
	v_lshl_add_u64 v[152:153], v[168:169], 1, v[152:153]
	global_store_dwordx4 v[152:153], v[144:147], off

; #define LAS __attribute__((address_space(3)))
;     __device__ __forceinline__ void operator()(f32x4 (&acc)[2][2][4][2], const Unit& u, int wr, int wc, int fr, int fq) const {
;     ...
;         for (int ai = 0; ai < 2; ++ai)
; #pragma unroll
;             for (int m = 0; m < 4; ++m) { const float rs = RS[wr * 64 + fr + ai * HALF + m * 16];
; #pragma unroll
;                 for (int bj = 0; bj < 2; ++bj)
; #pragma unroll
;                     for (int n = 0; n < 2; ++n) acc[ai][bj][m][n] *= rs; }
;         LAS float* XF = X; LAS float* XL = X + 4 * 128;
; #pragma unroll
;         for (int ai = 0; ai < 2; ++ai) { const int rb = 2 * ai + wr;
;             if (fr == 0) { *(LAS f32x4*)(XF + rb * 128 + cl) = acc[ai][0][0][0]; *(LAS f32x4*)(XF + rb * 128 + cl + 4) = acc[ai][0][0][1]; }
;             if (fr == 15) { *(LAS f32x4*)(XL + rb * 128 + cl) = acc[ai][0][3][0]; *(LAS f32x4*)(XL + rb * 128 + cl + 4) = acc[ai][0][3][1]; } }
;         asm volatile("s_waitcnt lgkmcnt(0)" ::: "memory"); __builtin_amdgcn_s_barrier(); asm volatile("" ::: "memory");
; #pragma unroll
;         for (int ai = 0; ai < 2; ++ai) {
;             const int rb = 2 * ai + wr;
;             f32x4 Sprev[2], Scur[2], Tcur[2], Tnext[2];
; #pragma unroll
;             for (int n = 0; n < 2; ++n) { Sprev[n] = (rb > 0) ? *(const LAS f32x4*)(XL + (rb - 1) * 128 + cl + 4 * n) : (f32x4){0.f, 0.f, 0.f, 0.f};
; #pragma unroll
;                 for (int j = 0; j < 4; ++j) Tcur[n][j] = dpp_rol1(acc[ai][0][0][n][j]); }
; #pragma unroll
;             for (int m = 0; m < 4; ++m) {
; #pragma unroll
;                 for (int n = 0; n < 2; ++n) {
; #pragma unroll
;                     for (int j = 0; j < 4; ++j) Scur[n][j] = dpp_ror1(acc[ai][0][m][n][j]);
;                     if (m < 3) {
; #pragma unroll
;                         for (int j = 0; j < 4; ++j) Tnext[n][j] = dpp_rol1(acc[ai][0][m < 3 ? m + 1 : 3][n][j]);
;                     } else Tnext[n] = (rb < 3) ? *(const LAS f32x4*)(XF + (rb + 1) * 128 + cl + 4 * n) : (f32x4){0.f, 0.f, 0.f, 0.f};
;                 }
;                 const int row = row0 + ai * HALF + m * 16, lrow = row & 255;
;                 const bool edge = (lrow == 0) || (lrow == 255);
;                 u32x4 ow;
; #pragma unroll
;                 for (int n = 0; n < 2; ++n) {
;                     const f32x4 up = (fr == 0) ? Sprev[n] : Scur[n], dn = (fr == 15) ? Tnext[n] : Tcur[n];
.LBB0_2056:
	s_or_b64 exec, exec, s[14:15]
	v_mov_b32_e32 v136, v208
	v_mov_b32_e32 v137, v208
	v_mov_b32_dpp v152, v172 row_ror:1 row_mask:0xf bank_mask:0xf
	v_mov_b32_dpp v153, v173 row_ror:1 row_mask:0xf bank_mask:0xf
	v_pk_mul_f32 v[138:139], v[118:119], v[136:137]
	v_pk_mul_f32 v[136:137], v[114:115], v[136:137]
	v_pk_mul_f32 v[124:125], v[124:125], v[206:207] op_sel_hi:[1,0]
	v_pk_mul_f32 v[114:115], v[122:123], v[206:207] op_sel_hi:[1,0]
	v_cndmask_b32_e64 v123, v153, v237, s[2:3]
	v_cndmask_b32_e64 v122, v152, v236, s[2:3]
	v_mov_b32_dpp v156, v124 row_ror:15 row_mask:0xf bank_mask:0xf
	v_mov_b32_dpp v157, v125 row_ror:15 row_mask:0xf bank_mask:0xf
	v_pk_mul_f32 v[122:123], v[84:85], v[122:123]
	v_cndmask_b32_e64 v143, v240, v157, s[4:5]
	v_cndmask_b32_e64 v142, v238, v156, s[4:5]
	v_pk_fma_f32 v[122:123], v[80:81], v[172:173], v[122:123]
	v_pk_fma_f32 v[122:123], v[68:69], v[142:143], v[122:123]
	v_pk_add_f32 v[122:123], v[76:77], v[122:123]
	v_mov_b32_e32 v209, v208
	v_mul_f32_e32 v142, v122, v122
	v_fmamk_f32 v142, v142, 0xbdd2d3e7, v232
	v_mul_f32_e32 v143, v123, v123
	v_mul_f32_e32 v142, v122, v142
	v_fmamk_f32 v143, v143, 0xbdd2d3e7, v232
	v_mov_b32_dpp v154, v170 row_ror:1 row_mask:0xf bank_mask:0xf
	v_mov_b32_dpp v155, v171 row_ror:1 row_mask:0xf bank_mask:0xf
	v_exp_f32_e32 v142, v142
	v_mul_f32_e32 v143, v123, v143
	v_pk_mul_f32 v[140:141], v[116:117], v[208:209]
	v_pk_mul_f32 v[118:119], v[126:127], v[206:207] op_sel_hi:[1,0]
	v_pk_mul_f32 v[116:117], v[120:121], v[206:207] op_sel_hi:[1,0]
	v_cndmask_b32_e64 v121, v155, v241, s[2:3]
	v_cndmask_b32_e64 v120, v154, v239, s[2:3]
	v_exp_f32_e32 v143, v143
	v_mov_b32_dpp v158, v118 row_ror:15 row_mask:0xf bank_mask:0xf
	v_mov_b32_dpp v159, v119 row_ror:15 row_mask:0xf bank_mask:0xf
	v_pk_mul_f32 v[120:121], v[86:87], v[120:121]
	v_cndmask_b32_e64 v127, v243, v159, s[4:5]
	v_cndmask_b32_e64 v126, v242, v158, s[4:5]
	v_pk_fma_f32 v[120:121], v[82:83], v[170:171], v[120:121]
	v_pk_fma_f32 v[120:121], v[70:71], v[126:127], v[120:121]
	v_add_f32_e32 v126, 1.0, v142
	v_rcp_f32_e32 v142, v126
	v_add_f32_e32 v126, 1.0, v143
	v_rcp_f32_e32 v143, v126
	v_pk_add_f32 v[126:127], v[78:79], v[120:121]
	v_mul_f32_e32 v120, v122, v142
	v_mul_f32_e32 v122, v126, v126
	v_mul_f32_e32 v121, v123, v143
	v_mul_f32_e32 v123, v127, v127
	v_fmamk_f32 v122, v122, 0xbdd2d3e7, v232
	v_fmamk_f32 v123, v123, 0xbdd2d3e7, v232
	v_mul_f32_e32 v122, v126, v122
	v_mul_f32_e32 v123, v127, v123
	v_exp_f32_e32 v122, v122
	v_exp_f32_e32 v123, v123
	v_mov_b32_dpp v160, v150 row_ror:1 row_mask:0xf bank_mask:0xf
	v_add_f32_e32 v122, 1.0, v122
	v_add_f32_e32 v123, 1.0, v123
	v_rcp_f32_e32 v122, v122
	v_rcp_f32_e32 v123, v123
	v_mov_b32_dpp v161, v151 row_ror:1 row_mask:0xf bank_mask:0xf
	v_mul_f32_e32 v120, v140, v120
	v_mul_f32_e32 v121, v141, v121
	v_cvt_pk_bf16_f32 v120, v120, v121
	v_mul_f32_e32 v121, v126, v122
	v_mul_f32_e32 v122, v127, v123
	v_cndmask_b32_e64 v127, v161, v199, s[2:3]
	v_cndmask_b32_e64 v126, v160, v175, s[2:3]
	v_mov_b32_dpp v164, v116 row_ror:15 row_mask:0xf bank_mask:0xf
	v_mov_b32_dpp v165, v117 row_ror:15 row_mask:0xf bank_mask:0xf
	v_pk_mul_f32 v[126:127], v[44:45], v[126:127]
	v_cndmask_b32_e64 v141, v210, v165, s[4:5]
	v_cndmask_b32_e64 v140, v201, v164, s[4:5]
	v_pk_fma_f32 v[126:127], v[40:41], v[150:151], v[126:127]
	v_pk_fma_f32 v[126:127], v[32:33], v[140:141], v[126:127]
	v_pk_add_f32 v[126:127], v[36:37], v[126:127]
	v_mov_b32_dpp v162, v148 row_ror:1 row_mask:0xf bank_mask:0xf
	v_mul_f32_e32 v140, v126, v126
	v_fmamk_f32 v140, v140, 0xbdd2d3e7, v232
	v_mul_f32_e32 v140, v126, v140
	v_mul_f32_e32 v141, v127, v127
	v_mov_b32_dpp v163, v149 row_ror:1 row_mask:0xf bank_mask:0xf
	v_mul_f32_e32 v121, v138, v121
	v_mul_f32_e32 v122, v139, v122
	v_exp_f32_e32 v140, v140
	v_fmamk_f32 v141, v141, 0xbdd2d3e7, v232
	v_cvt_pk_bf16_f32 v121, v121, v122
	v_cndmask_b32_e64 v123, v163, v211, s[2:3]
	v_cndmask_b32_e64 v122, v162, v207, s[2:3]
	v_mul_f32_e32 v141, v127, v141
	v_mov_b32_dpp v166, v114 row_ror:15 row_mask:0xf bank_mask:0xf
	v_mov_b32_dpp v167, v115 row_ror:15 row_mask:0xf bank_mask:0xf
	v_pk_mul_f32 v[122:123], v[46:47], v[122:123]
	v_exp_f32_e32 v141, v141
	v_cndmask_b32_e64 v139, v235, v167, s[4:5]
	v_cndmask_b32_e64 v138, v234, v166, s[4:5]
	v_pk_fma_f32 v[122:123], v[42:43], v[148:149], v[122:123]
	v_pk_mul_f32 v[112:113], v[112:113], v[208:209]
	v_pk_fma_f32 v[122:123], v[34:35], v[138:139], v[122:123]
	v_add_f32_e32 v138, 1.0, v140
	v_rcp_f32_e32 v140, v138
	v_add_f32_e32 v138, 1.0, v141
	v_rcp_f32_e32 v141, v138
	v_pk_add_f32 v[138:139], v[38:39], v[122:123]
	v_mul_f32_e32 v122, v126, v140
	v_mul_f32_e32 v123, v138, v138
	v_fmamk_f32 v123, v123, 0xbdd2d3e7, v232
	v_mul_f32_e32 v126, v139, v139
	v_mul_f32_e32 v123, v138, v123
	v_fmamk_f32 v126, v126, 0xbdd2d3e7, v232
	v_exp_f32_e32 v123, v123
	v_mul_f32_e32 v126, v139, v126
	v_exp_f32_e32 v126, v126
	v_mul_f32_e32 v112, v112, v122
	v_mul_f32_e32 v122, v127, v141
	v_mul_f32_e32 v113, v113, v122
	v_add_f32_e32 v122, 1.0, v123
	v_rcp_f32_e32 v123, v122
	v_add_f32_e32 v122, 1.0, v126
	v_rcp_f32_e32 v126, v122
	v_cvt_pk_bf16_f32 v122, v112, v113
	v_mul_f32_e32 v112, v138, v123
	v_mul_f32_e32 v113, v139, v126
	v_mov_b32_dpp v138, v124 row_ror:1 row_mask:0xf bank_mask:0xf
	v_mov_b32_dpp v139, v125 row_ror:1 row_mask:0xf bank_mask:0xf
	v_cndmask_b32_e64 v151, v139, v153, s[2:3]
	v_cndmask_b32_e64 v150, v138, v152, s[2:3]
	v_mov_b32_dpp v141, v118 row_ror:1 row_mask:0xf bank_mask:0xf
	v_mov_b32_dpp v143, v119 row_ror:1 row_mask:0xf bank_mask:0xf
	v_mov_b32_dpp v140, v128 row_ror:15 row_mask:0xf bank_mask:0xf
; #define LAS __attribute__((address_space(3)))
;     __device__ __forceinline__ void operator()(f32x4 (&acc)[2][2][4][2], const Unit& u, int wr, int wc, int fr, int fq) const {
;     ...
;         for (int ai = 0; ai < 2; ++ai)
; #pragma unroll
;             for (int m = 0; m < 4; ++m) { const float rs = RS[wr * 64 + fr + ai * HALF + m * 16];
; #pragma unroll
;                 for (int bj = 0; bj < 2; ++bj)
; #pragma unroll
;                     for (int n = 0; n < 2; ++n) acc[ai][bj][m][n] *= rs; }
;         LAS float* XF = X; LAS float* XL = X + 4 * 128;
; #pragma unroll
;         for (int ai = 0; ai < 2; ++ai) { const int rb = 2 * ai + wr;
;             if (fr == 0) { *(LAS f32x4*)(XF + rb * 128 + cl) = acc[ai][0][0][0]; *(LAS f32x4*)(XF + rb * 128 + cl + 4) = acc[ai][0][0][1]; }
;             if (fr == 15) { *(LAS f32x4*)(XL + rb * 128 + cl) = acc[ai][0][3][0]; *(LAS f32x4*)(XL + rb * 128 + cl + 4) = acc[ai][0][3][1]; } }
;         asm volatile("s_waitcnt lgkmcnt(0)" ::: "memory"); __builtin_amdgcn_s_barrier(); asm volatile("" ::: "memory");
; #pragma unroll
;         for (int ai = 0; ai < 2; ++ai) {
;             const int rb = 2 * ai + wr;
;             f32x4 Sprev[2], Scur[2], Tcur[2], Tnext[2];
; #pragma unroll
;             for (int n = 0; n < 2; ++n) { Sprev[n] = (rb > 0) ? *(const LAS f32x4*)(XL + (rb - 1) * 128 + cl + 4 * n) : (f32x4){0.f, 0.f, 0.f, 0.f};
; #pragma unroll
;                 for (int j = 0; j < 4; ++j) Tcur[n][j] = dpp_rol1(acc[ai][0][0][n][j]); }
; #pragma unroll
;             for (int m = 0; m < 4; ++m) {
; #pragma unroll
;                 for (int n = 0; n < 2; ++n) {
; #pragma unroll
;                     for (int j = 0; j < 4; ++j) Scur[n][j] = dpp_ror1(acc[ai][0][m][n][j]);
;                     if (m < 3) {
; #pragma unroll
;                         for (int j = 0; j < 4; ++j) Tnext[n][j] = dpp_rol1(acc[ai][0][m < 3 ? m + 1 : 3][n][j]);
;                     } else Tnext[n] = (rb < 3) ? *(const LAS f32x4*)(XF + (rb + 1) * 128 + cl + 4 * n) : (f32x4){0.f, 0.f, 0.f, 0.f};
;                 }
;                 const int row = row0 + ai * HALF + m * 16, lrow = row & 255;
;                 const bool edge = (lrow == 0) || (lrow == 255);
;                 u32x4 ow;
; #pragma unroll
;                 for (int n = 0; n < 2; ++n) {
;                     const f32x4 up = (fr == 0) ? Sprev[n] : Scur[n], dn = (fr == 15) ? Tnext[n] : Tcur[n];
	v_mov_b32_dpp v142, v129 row_ror:15 row_mask:0xf bank_mask:0xf
	v_pk_mul_f32 v[150:151], v[84:85], v[150:151]
	v_cndmask_b32_e64 v149, v143, v155, s[2:3]
	v_cndmask_b32_e64 v148, v141, v154, s[2:3]
	v_cndmask_b32_e64 v155, v157, v142, s[4:5]
	v_cndmask_b32_e64 v154, v156, v140, s[4:5]
	v_pk_fma_f32 v[124:125], v[80:81], v[124:125], v[150:151]
	v_pk_mul_f32 v[148:149], v[86:87], v[148:149]
	v_pk_fma_f32 v[124:125], v[68:69], v[154:155], v[124:125]
	v_pk_fma_f32 v[118:119], v[82:83], v[118:119], v[148:149]
	v_pk_add_f32 v[124:125], v[76:77], v[124:125]
	v_readlane_b32 s14, v254, 15
	v_mul_f32_e32 v148, v124, v124
	v_fmamk_f32 v148, v148, 0xbdd2d3e7, v232
	v_mul_f32_e32 v149, v125, v125
	v_mul_f32_e32 v148, v124, v148
	v_fmamk_f32 v149, v149, 0xbdd2d3e7, v232
	v_exp_f32_e32 v148, v148
	v_mul_f32_e32 v149, v125, v149
	v_exp_f32_e32 v149, v149
	v_readlane_b32 s15, v254, 16
	v_or_b32_e32 v144, 16, v174
	v_add_f32_e32 v148, 1.0, v148
	v_mov_b64_e32 v[146:147], s[14:15]
	v_mad_i64_i32 v[126:127], s[14:15], v144, s73, v[146:147]
	v_rcp_f32_e32 v148, v148
	v_add_f32_e32 v149, 1.0, v149
	v_mov_b32_dpp v144, v130 row_ror:15 row_mask:0xf bank_mask:0xf
	v_mov_b32_dpp v145, v131 row_ror:15 row_mask:0xf bank_mask:0xf
	v_rcp_f32_e32 v149, v149
	v_cndmask_b32_e64 v153, v159, v145, s[4:5]
	v_cndmask_b32_e64 v152, v158, v144, s[4:5]
	v_pk_fma_f32 v[118:119], v[70:71], v[152:153], v[118:119]
	v_pk_mul_f32 v[108:109], v[108:109], v[206:207] op_sel_hi:[1,0]
	v_pk_add_f32 v[118:119], v[78:79], v[118:119]
	v_mul_f32_e32 v124, v124, v148
	v_mul_f32_e32 v108, v108, v124
	v_mul_f32_e32 v124, v125, v149
	v_mul_f32_e32 v125, v118, v118
	v_fmamk_f32 v125, v125, 0xbdd2d3e7, v232
	v_mul_f32_e32 v148, v119, v119
	v_mul_f32_e32 v125, v118, v125
	v_fmamk_f32 v148, v148, 0xbdd2d3e7, v232
	v_exp_f32_e32 v125, v125
	v_mul_f32_e32 v148, v119, v148
	v_exp_f32_e32 v148, v148
	v_mul_f32_e32 v109, v109, v124
	v_add_f32_e32 v124, 1.0, v125
	v_rcp_f32_e32 v124, v124
	v_add_f32_e32 v125, 1.0, v148
	v_mul_f32_e32 v112, v136, v112
	v_mul_f32_e32 v113, v137, v113
	v_rcp_f32_e32 v125, v125
	v_cvt_pk_bf16_f32 v123, v112, v113
	v_lshlrev_b64 v[112:113], 1, v[168:169]
	v_lshl_add_u64 v[126:127], v[126:127], 0, v[112:113]
	v_pk_mul_f32 v[110:111], v[110:111], v[206:207] op_sel_hi:[1,0]
	global_store_dwordx4 v[126:127], v[120:123], off
	v_cvt_pk_bf16_f32 v108, v108, v109
	v_mul_f32_e32 v109, v118, v124
	v_mul_f32_e32 v109, v110, v109
	v_mul_f32_e32 v110, v119, v125
	v_mov_b32_dpp v120, v116 row_ror:1 row_mask:0xf bank_mask:0xf
	v_mov_b32_dpp v121, v117 row_ror:1 row_mask:0xf bank_mask:0xf
	v_mov_b32_dpp v123, v114 row_ror:1 row_mask:0xf bank_mask:0xf
	v_mov_b32_dpp v127, v115 row_ror:1 row_mask:0xf bank_mask:0xf
	v_mul_f32_e32 v110, v111, v110
	v_cvt_pk_bf16_f32 v109, v109, v110
	v_cndmask_b32_e64 v111, v127, v163, s[2:3]
	v_cndmask_b32_e64 v110, v123, v162, s[2:3]
	v_cndmask_b32_e64 v119, v121, v161, s[2:3]
	v_cndmask_b32_e64 v118, v120, v160, s[2:3]
	v_mov_b32_dpp v122, v132 row_ror:15 row_mask:0xf bank_mask:0xf
	v_mov_b32_dpp v126, v133 row_ror:15 row_mask:0xf bank_mask:0xf
	v_pk_mul_f32 v[118:119], v[44:45], v[118:119]
	v_pk_mul_f32 v[110:111], v[46:47], v[110:111]
	v_cndmask_b32_e64 v149, v165, v126, s[4:5]
	v_cndmask_b32_e64 v148, v164, v122, s[4:5]
	v_pk_fma_f32 v[110:111], v[42:43], v[114:115], v[110:111]
	v_pk_fma_f32 v[114:115], v[40:41], v[116:117], v[118:119]
	v_pk_fma_f32 v[114:115], v[32:33], v[148:149], v[114:115]
	v_pk_add_f32 v[114:115], v[36:37], v[114:115]
	v_mov_b32_dpp v136, v134 row_ror:15 row_mask:0xf bank_mask:0xf
	v_mul_f32_e32 v116, v114, v114
	v_fmamk_f32 v116, v116, 0xbdd2d3e7, v232
	v_mul_f32_e32 v116, v114, v116
	v_mul_f32_e32 v117, v115, v115
	v_exp_f32_e32 v116, v116
	v_fmamk_f32 v117, v117, 0xbdd2d3e7, v232
	v_mul_f32_e32 v117, v115, v117
	v_exp_f32_e32 v117, v117
	v_mov_b32_dpp v137, v135 row_ror:15 row_mask:0xf bank_mask:0xf
	v_add_f32_e32 v116, 1.0, v116
	v_cndmask_b32_e64 v125, v167, v137, s[4:5]
	v_cndmask_b32_e64 v124, v166, v136, s[4:5]
	v_rcp_f32_e32 v118, v116
	v_pk_fma_f32 v[110:111], v[34:35], v[124:125], v[110:111]
	v_add_f32_e32 v116, 1.0, v117
	v_rcp_f32_e32 v119, v116
	v_pk_add_f32 v[116:117], v[38:39], v[110:111]
	v_mul_f32_e32 v110, v114, v118
	v_mul_f32_e32 v111, v116, v116
	v_fmamk_f32 v111, v111, 0xbdd2d3e7, v232
	v_mul_f32_e32 v114, v117, v117
	v_mul_f32_e32 v111, v116, v111
	v_fmamk_f32 v114, v114, 0xbdd2d3e7, v232
	v_exp_f32_e32 v111, v111
	v_mul_f32_e32 v114, v117, v114
	v_exp_f32_e32 v114, v114
	v_pk_mul_f32 v[104:105], v[104:105], v[206:207] op_sel_hi:[1,0]
	v_pk_mul_f32 v[106:107], v[106:107], v[206:207] op_sel_hi:[1,0]
	v_mul_f32_e32 v104, v104, v110
	v_mul_f32_e32 v110, v115, v119
	v_mul_f32_e32 v105, v105, v110
	v_add_f32_e32 v110, 1.0, v111
	v_rcp_f32_e32 v111, v110
	v_add_f32_e32 v110, 1.0, v114
	v_rcp_f32_e32 v114, v110
	v_cvt_pk_bf16_f32 v110, v104, v105
	v_mul_f32_e32 v104, v116, v111
	v_or_b32_e32 v170, 32, v174
	v_mul_f32_e32 v105, v117, v114
	v_mul_f32_e32 v104, v106, v104
	v_mul_f32_e32 v105, v107, v105
	v_cvt_pk_bf16_f32 v111, v104, v105
	v_mad_i64_i32 v[104:105], s[14:15], v170, s73, v[146:147]
	v_lshl_add_u64 v[104:105], v[104:105], 0, v[112:113]
	global_store_dwordx4 v[104:105], v[108:111], off
	v_cndmask_b32_e64 v105, 0, 1, s[36:37]
	v_mov_b32_dpp v119, v128 row_ror:1 row_mask:0xf bank_mask:0xf
	v_mov_b32_dpp v124, v129 row_ror:1 row_mask:0xf bank_mask:0xf
	v_mov_b32_dpp v125, v130 row_ror:1 row_mask:0xf bank_mask:0xf
	v_mov_b32_dpp v146, v131 row_ror:1 row_mask:0xf bank_mask:0xf
	v_mov_b32_e32 v104, 0
	v_cmp_ne_u32_e64 s[14:15], 1, v105
	s_andn2_b64 vcc, exec, s[36:37]
	v_mov_b32_e32 v108, 0
	v_mov_b32_e32 v109, 0
	v_mov_b32_e32 v110, 0
	v_mov_b32_e32 v111, 0
	s_cbranch_vccnz .LBB0_2058
	ds_read_b128 v[108:111], v225 offset:512

; #define LAS __attribute__((address_space(3)))
;     __device__ __forceinline__ void operator()(f32x4 (&acc)[2][2][4][2], const Unit& u, int wr, int wc, int fr, int fq) const {
;     ...
;         for (int ai = 0; ai < 2; ++ai)
; #pragma unroll
;             for (int m = 0; m < 4; ++m) { const float rs = RS[wr * 64 + fr + ai * HALF + m * 16];
; #pragma unroll
;                 for (int bj = 0; bj < 2; ++bj)
; #pragma unroll
;                     for (int n = 0; n < 2; ++n) acc[ai][bj][m][n] *= rs; }
;         LAS float* XF = X; LAS float* XL = X + 4 * 128;
; #pragma unroll
;         for (int ai = 0; ai < 2; ++ai) { const int rb = 2 * ai + wr;
;             if (fr == 0) { *(LAS f32x4*)(XF + rb * 128 + cl) = acc[ai][0][0][0]; *(LAS f32x4*)(XF + rb * 128 + cl + 4) = acc[ai][0][0][1]; }
;             if (fr == 15) { *(LAS f32x4*)(XL + rb * 128 + cl) = acc[ai][0][3][0]; *(LAS f32x4*)(XL + rb * 128 + cl + 4) = acc[ai][0][3][1]; } }
;         asm volatile("s_waitcnt lgkmcnt(0)" ::: "memory"); __builtin_amdgcn_s_barrier(); asm volatile("" ::: "memory");
; #pragma unroll
;         for (int ai = 0; ai < 2; ++ai) {
;             const int rb = 2 * ai + wr;
;             f32x4 Sprev[2], Scur[2], Tcur[2], Tnext[2];
; #pragma unroll
;             for (int n = 0; n < 2; ++n) { Sprev[n] = (rb > 0) ? *(const LAS f32x4*)(XL + (rb - 1) * 128 + cl + 4 * n) : (f32x4){0.f, 0.f, 0.f, 0.f};
; #pragma unroll
;                 for (int j = 0; j < 4; ++j) Tcur[n][j] = dpp_rol1(acc[ai][0][0][n][j]); }
; #pragma unroll
;             for (int m = 0; m < 4; ++m) {
; #pragma unroll
;                 for (int n = 0; n < 2; ++n) {
; #pragma unroll
;                     for (int j = 0; j < 4; ++j) Scur[n][j] = dpp_ror1(acc[ai][0][m][n][j]);
;                     if (m < 3) {
; #pragma unroll
;                         for (int j = 0; j < 4; ++j) Tnext[n][j] = dpp_rol1(acc[ai][0][m < 3 ? m + 1 : 3][n][j]);
;                     } else Tnext[n] = (rb < 3) ? *(const LAS f32x4*)(XF + (rb + 1) * 128 + cl + 4 * n) : (f32x4){0.f, 0.f, 0.f, 0.f};
;                 }
;                 const int row = row0 + ai * HALF + m * 16, lrow = row & 255;
;                 const bool edge = (lrow == 0) || (lrow == 255);
;                 u32x4 ow;
; #pragma unroll
;                 for (int n = 0; n < 2; ++n) {
;                     const f32x4 up = (fr == 0) ? Sprev[n] : Scur[n], dn = (fr == 15) ? Tnext[n] : Tcur[n];
.LBB0_2069:
	v_pk_mul_f32 v[106:107], v[72:73], v[200:201] op_sel_hi:[1,0]
	v_mov_b32_dpp v118, v96 row_ror:1 row_mask:0xf bank_mask:0xf
	v_mov_b32_dpp v119, v97 row_ror:1 row_mask:0xf bank_mask:0xf
	v_pk_mul_f32 v[72:73], v[66:67], v[200:201] op_sel_hi:[1,0]
	s_waitcnt lgkmcnt(0)
	v_cndmask_b32_e64 v67, v119, v93, s[2:3]
	v_cndmask_b32_e64 v66, v118, v92, s[2:3]
	v_mov_b32_e32 v104, v202
	v_mov_b32_e32 v105, v202
	v_mov_b32_dpp v121, v98 row_ror:1 row_mask:0xf bank_mask:0xf
	v_mov_b32_dpp v123, v99 row_ror:1 row_mask:0xf bank_mask:0xf
	v_mov_b32_dpp v120, v106 row_ror:15 row_mask:0xf bank_mask:0xf
	v_mov_b32_dpp v122, v107 row_ror:15 row_mask:0xf bank_mask:0xf
	v_pk_mul_f32 v[66:67], v[84:85], v[66:67]
	v_pk_mul_f32 v[62:63], v[62:63], v[104:105]
	v_pk_mul_f32 v[58:59], v[58:59], v[104:105]
	v_pk_mul_f32 v[104:105], v[74:75], v[200:201] op_sel_hi:[1,0]
	v_pk_mul_f32 v[74:75], v[64:65], v[200:201] op_sel_hi:[1,0]
	v_cndmask_b32_e64 v65, v123, v95, s[2:3]
	v_cndmask_b32_e64 v64, v121, v94, s[2:3]
	v_cndmask_b32_e64 v95, v129, v122, s[4:5]
	v_cndmask_b32_e64 v94, v128, v120, s[4:5]
	v_pk_fma_f32 v[66:67], v[80:81], v[96:97], v[66:67]
	v_pk_fma_f32 v[66:67], v[68:69], v[94:95], v[66:67]
	v_pk_add_f32 v[66:67], v[76:77], v[66:67]
	v_mov_b32_dpp v124, v104 row_ror:15 row_mask:0xf bank_mask:0xf
	v_mul_f32_e32 v94, v66, v66
	v_fmamk_f32 v94, v94, 0xbdd2d3e7, v232
	v_mul_f32_e32 v95, v67, v67
	v_mul_f32_e32 v94, v66, v94
	v_fmamk_f32 v95, v95, 0xbdd2d3e7, v232
	v_exp_f32_e32 v94, v94
	v_mul_f32_e32 v95, v67, v95
	v_exp_f32_e32 v95, v95
	v_mov_b32_dpp v125, v105 row_ror:15 row_mask:0xf bank_mask:0xf
	v_pk_mul_f32 v[64:65], v[86:87], v[64:65]
	v_cndmask_b32_e64 v93, v131, v125, s[4:5]
	v_cndmask_b32_e64 v92, v130, v124, s[4:5]
	v_pk_fma_f32 v[64:65], v[82:83], v[98:99], v[64:65]
	v_pk_fma_f32 v[64:65], v[70:71], v[92:93], v[64:65]
	v_add_f32_e32 v92, 1.0, v94
	v_rcp_f32_e32 v94, v92
	v_add_f32_e32 v92, 1.0, v95
	v_rcp_f32_e32 v95, v92
	v_pk_add_f32 v[92:93], v[78:79], v[64:65]
	v_mul_f32_e32 v64, v66, v94
	v_mul_f32_e32 v66, v92, v92
	v_mul_f32_e32 v65, v67, v95
	v_mul_f32_e32 v67, v93, v93
	v_fmamk_f32 v66, v66, 0xbdd2d3e7, v232
	v_fmamk_f32 v67, v67, 0xbdd2d3e7, v232
	v_mul_f32_e32 v66, v92, v66
	v_mul_f32_e32 v67, v93, v67
	v_exp_f32_e32 v66, v66
	v_exp_f32_e32 v67, v67
	v_mov_b32_dpp v108, v100 row_ror:1 row_mask:0xf bank_mask:0xf
	v_add_f32_e32 v66, 1.0, v66
	v_add_f32_e32 v67, 1.0, v67
	v_rcp_f32_e32 v66, v66
	v_rcp_f32_e32 v67, v67
	v_mov_b32_dpp v109, v101 row_ror:1 row_mask:0xf bank_mask:0xf
	v_pk_mul_f32 v[60:61], v[60:61], v[202:203]
	v_cndmask_b32_e64 v89, v109, v89, s[2:3]
	v_cndmask_b32_e64 v88, v108, v88, s[2:3]
	v_mov_b32_dpp v132, v100 row_ror:15 row_mask:0xf bank_mask:0xf
	v_mov_b32_dpp v133, v101 row_ror:15 row_mask:0xf bank_mask:0xf
	v_mov_b32_dpp v110, v74 row_ror:15 row_mask:0xf bank_mask:0xf
	v_mov_b32_dpp v114, v75 row_ror:15 row_mask:0xf bank_mask:0xf
	v_mul_f32_e32 v64, v60, v64
	v_mul_f32_e32 v65, v61, v65
	v_pk_mul_f32 v[88:89], v[44:45], v[88:89]
	v_cvt_pk_bf16_f32 v64, v64, v65
	v_mul_f32_e32 v65, v92, v66
	v_mul_f32_e32 v66, v93, v67
	v_cndmask_b32_e64 v93, v133, v114, s[4:5]
	v_cndmask_b32_e64 v92, v132, v110, s[4:5]
	v_pk_fma_f32 v[88:89], v[40:41], v[100:101], v[88:89]
	v_pk_fma_f32 v[88:89], v[32:33], v[92:93], v[88:89]
	v_pk_add_f32 v[88:89], v[36:37], v[88:89]
	v_mov_b32_dpp v111, v102 row_ror:1 row_mask:0xf bank_mask:0xf
	v_mul_f32_e32 v92, v88, v88
	v_fmamk_f32 v92, v92, 0xbdd2d3e7, v232
	v_mul_f32_e32 v93, v89, v89
	v_mul_f32_e32 v92, v88, v92
	v_fmamk_f32 v93, v93, 0xbdd2d3e7, v232
	v_mov_b32_dpp v115, v103 row_ror:1 row_mask:0xf bank_mask:0xf
	v_mul_f32_e32 v65, v62, v65
	v_mul_f32_e32 v66, v63, v66
	v_exp_f32_e32 v92, v92
	v_mul_f32_e32 v93, v89, v93
	v_cvt_pk_bf16_f32 v65, v65, v66
	v_cndmask_b32_e64 v67, v115, v91, s[2:3]
	v_cndmask_b32_e64 v66, v111, v90, s[2:3]
	v_exp_f32_e32 v93, v93
	v_mov_b32_dpp v134, v102 row_ror:15 row_mask:0xf bank_mask:0xf
	v_mov_b32_dpp v135, v103 row_ror:15 row_mask:0xf bank_mask:0xf
	v_mov_b32_dpp v116, v72 row_ror:15 row_mask:0xf bank_mask:0xf
	v_mov_b32_dpp v117, v73 row_ror:15 row_mask:0xf bank_mask:0xf
	v_pk_mul_f32 v[66:67], v[46:47], v[66:67]
	v_cndmask_b32_e64 v91, v135, v117, s[4:5]
	v_cndmask_b32_e64 v90, v134, v116, s[4:5]
	v_pk_fma_f32 v[66:67], v[42:43], v[102:103], v[66:67]
	v_pk_mul_f32 v[56:57], v[56:57], v[202:203]
	v_pk_fma_f32 v[66:67], v[34:35], v[90:91], v[66:67]
	v_add_f32_e32 v90, 1.0, v92
	v_rcp_f32_e32 v92, v90
	v_add_f32_e32 v90, 1.0, v93
	v_rcp_f32_e32 v93, v90
	v_pk_add_f32 v[90:91], v[38:39], v[66:67]
	v_mul_f32_e32 v66, v88, v92
	v_mul_f32_e32 v88, v90, v90
	v_mul_f32_e32 v67, v89, v93
	v_fmamk_f32 v88, v88, 0xbdd2d3e7, v232
	v_mul_f32_e32 v89, v91, v91
	v_mul_f32_e32 v88, v90, v88
	v_fmamk_f32 v89, v89, 0xbdd2d3e7, v232
	v_exp_f32_e32 v88, v88
	v_mul_f32_e32 v89, v91, v89
	v_exp_f32_e32 v89, v89
	v_add_u32_e32 v126, 0x80, v174
	v_add_f32_e32 v88, 1.0, v88
	v_rcp_f32_e32 v88, v88
	v_add_f32_e32 v89, 1.0, v89
	v_rcp_f32_e32 v89, v89
	v_mul_f32_e32 v66, v56, v66
	v_mul_f32_e32 v67, v57, v67
	v_and_b32_e32 v127, 0xcf, v126
	v_cvt_pk_bf16_f32 v66, v66, v67
	v_mul_f32_e32 v67, v90, v88
	v_mul_f32_e32 v67, v58, v67
	v_mul_f32_e32 v88, v91, v89
	v_cmp_eq_u32_e32 vcc, 0, v127
	v_cmp_ne_u32_e64 s[14:15], 0, v127
	v_mul_f32_e32 v88, v59, v88
	v_cvt_pk_bf16_f32 v67, v67, v88
	s_and_saveexec_b64 s[52:53], s[14:15]
	s_cbranch_execz .LBB0_2071
	v_readlane_b32 s14, v254, 15
	v_readlane_b32 s15, v254, 16
	s_nop 1
	v_mov_b64_e32 v[88:89], s[14:15]
	v_mad_i64_i32 v[88:89], s[14:15], v126, s73, v[88:89]
	v_lshl_add_u64 v[88:89], v[168:169], 1, v[88:89]
	global_store_dwordx4 v[88:89], v[64:67], off

; #define LAS __attribute__((address_space(3)))
; __device__ __forceinline__ unsigned cvt_pk_bf16(float lo, float hi) { unsigned r; asm volatile("v_cvt_pk_bf16_f32 %0, %1, %2" : "=v"(r) : "v"(lo), "v"(hi)); return r; }
; __device__ __forceinline__ float dpp_ror1(float v) { return __int_as_float(__builtin_amdgcn_update_dpp(0, __float_as_int(v), 0x121, 0xf, 0xf, false)); }
; __device__ __forceinline__ float dpp_rol1(float v) { return __int_as_float(__builtin_amdgcn_update_dpp(0, __float_as_int(v), 0x12F, 0xf, 0xf, false)); }
; __device__ __forceinline__ float gelu_tanh(float x) {
;     constexpr float C1 = -2.0f * 1.4426950408889634f * 0.7978845608028654f, C2 = C1 * 0.044715f;
;     const float e = __builtin_amdgcn_exp2f(x * fmaf(x * x, C2, C1));
;     return x * __builtin_amdgcn_rcpf(1.0f + e);
; }
;     __device__ __forceinline__ void operator()(f32x4 (&acc)[2][2][4][2], const Unit& u, int wr, int wc, int fr, int fq) const {
;     ...
;             for (int m = 0; m < 4; ++m) {
; #pragma unroll
;                 for (int n = 0; n < 2; ++n) {
; #pragma unroll
;                     for (int j = 0; j < 4; ++j) Scur[n][j] = dpp_ror1(acc[ai][0][m][n][j]);
;                     if (m < 3) {
; #pragma unroll
;                         for (int j = 0; j < 4; ++j) Tnext[n][j] = dpp_rol1(acc[ai][0][m < 3 ? m + 1 : 3][n][j]);
;                     } else Tnext[n] = (rb < 3) ? *(const LAS f32x4*)(XF + (rb + 1) * 128 + cl + 4 * n) : (f32x4){0.f, 0.f, 0.f, 0.f};
;                 }
;                 const int row = row0 + ai * HALF + m * 16, lrow = row & 255;
;                 const bool edge = (lrow == 0) || (lrow == 255);
;                 u32x4 ow;
; #pragma unroll
;                 for (int n = 0; n < 2; ++n) {
;                     const f32x4 up = (fr == 0) ? Sprev[n] : Scur[n], dn = (fr == 15) ? Tnext[n] : Tcur[n];
;                     const f32x4 a = w0[n] * up + w1[n] * acc[ai][0][m][n] + w2[n] * dn + bb[n];
;                     const f32x4 uu = acc[ai][1][m][n];
;                     ow[2 * n] = cvt_pk_bf16(gelu_tanh(a[0]) * uu[0], gelu_tanh(a[1]) * uu[1]);
;                     ow[2 * n + 1] = cvt_pk_bf16(gelu_tanh(a[2]) * uu[2], gelu_tanh(a[3]) * uu[3]);
;                 }
.LBB0_2074:
	s_or_b64 exec, exec, s[52:53]
	v_mov_b32_e32 v201, v200
	v_mov_b32_e32 v56, v200
	v_mov_b32_e32 v57, v200
	v_mov_b32_dpp v88, v106 row_ror:1 row_mask:0xf bank_mask:0xf
	v_mov_b32_dpp v89, v107 row_ror:1 row_mask:0xf bank_mask:0xf
	v_pk_mul_f32 v[58:59], v[22:23], v[56:57]
	v_pk_mul_f32 v[62:63], v[16:17], v[200:201]
	v_pk_mul_f32 v[22:23], v[28:29], v[198:199] op_sel_hi:[1,0]
	v_pk_mul_f32 v[16:17], v[26:27], v[198:199] op_sel_hi:[1,0]
	v_cndmask_b32_e64 v27, v89, v119, s[2:3]
	v_cndmask_b32_e64 v26, v88, v118, s[2:3]
	v_mov_b32_dpp v90, v22 row_ror:15 row_mask:0xf bank_mask:0xf
	v_mov_b32_dpp v91, v23 row_ror:15 row_mask:0xf bank_mask:0xf
	v_pk_mul_f32 v[26:27], v[84:85], v[26:27]
	v_pk_mul_f32 v[60:61], v[20:21], v[200:201]
	v_pk_mul_f32 v[20:21], v[30:31], v[198:199] op_sel_hi:[1,0]
	v_cndmask_b32_e64 v31, v122, v91, s[4:5]
	v_cndmask_b32_e64 v30, v120, v90, s[4:5]
	v_pk_fma_f32 v[26:27], v[80:81], v[106:107], v[26:27]
	v_pk_fma_f32 v[26:27], v[68:69], v[30:31], v[26:27]
	v_pk_add_f32 v[26:27], v[76:77], v[26:27]
	v_mov_b32_dpp v66, v104 row_ror:1 row_mask:0xf bank_mask:0xf
	v_mul_f32_e32 v30, v26, v26
	v_fmamk_f32 v30, v30, 0xbdd2d3e7, v232
	v_mul_f32_e32 v31, v27, v27
	v_mul_f32_e32 v30, v26, v30
	v_fmamk_f32 v31, v31, 0xbdd2d3e7, v232
	v_mov_b32_dpp v67, v105 row_ror:1 row_mask:0xf bank_mask:0xf
	v_exp_f32_e32 v30, v30
	v_mul_f32_e32 v31, v27, v31
	v_pk_mul_f32 v[56:57], v[18:19], v[56:57]
	v_pk_mul_f32 v[18:19], v[24:25], v[198:199] op_sel_hi:[1,0]
	v_cndmask_b32_e64 v25, v67, v123, s[2:3]
	v_cndmask_b32_e64 v24, v66, v121, s[2:3]
	v_exp_f32_e32 v31, v31
	v_mov_b32_dpp v92, v20 row_ror:15 row_mask:0xf bank_mask:0xf
	v_mov_b32_dpp v93, v21 row_ror:15 row_mask:0xf bank_mask:0xf
	v_pk_mul_f32 v[24:25], v[86:87], v[24:25]
	v_cndmask_b32_e64 v29, v125, v93, s[4:5]
	v_cndmask_b32_e64 v28, v124, v92, s[4:5]
	v_pk_fma_f32 v[24:25], v[82:83], v[104:105], v[24:25]
	v_pk_fma_f32 v[24:25], v[70:71], v[28:29], v[24:25]
	v_add_f32_e32 v28, 1.0, v30
	v_rcp_f32_e32 v30, v28
	v_add_f32_e32 v28, 1.0, v31
	v_rcp_f32_e32 v31, v28
	v_pk_add_f32 v[28:29], v[78:79], v[24:25]
	v_mul_f32_e32 v24, v26, v30
	v_mul_f32_e32 v26, v28, v28
	v_mul_f32_e32 v25, v27, v31
	v_mul_f32_e32 v27, v29, v29
	v_fmamk_f32 v26, v26, 0xbdd2d3e7, v232
	v_fmamk_f32 v27, v27, 0xbdd2d3e7, v232
	v_mul_f32_e32 v26, v28, v26
	v_mul_f32_e32 v27, v29, v27
	v_exp_f32_e32 v26, v26
	v_exp_f32_e32 v27, v27
	v_mov_b32_dpp v94, v74 row_ror:1 row_mask:0xf bank_mask:0xf
	v_add_f32_e32 v26, 1.0, v26
	v_add_f32_e32 v27, 1.0, v27
	v_rcp_f32_e32 v26, v26
	v_rcp_f32_e32 v27, v27
	v_mov_b32_dpp v95, v75 row_ror:1 row_mask:0xf bank_mask:0xf
	v_mul_f32_e32 v24, v60, v24
	v_mul_f32_e32 v25, v61, v25
	v_cvt_pk_bf16_f32 v24, v24, v25
	v_mul_f32_e32 v25, v28, v26
	v_mul_f32_e32 v26, v29, v27
	v_cndmask_b32_e64 v29, v95, v109, s[2:3]
	v_cndmask_b32_e64 v28, v94, v108, s[2:3]
	v_mov_b32_dpp v98, v18 row_ror:15 row_mask:0xf bank_mask:0xf
	v_mov_b32_dpp v99, v19 row_ror:15 row_mask:0xf bank_mask:0xf
	v_pk_mul_f32 v[28:29], v[44:45], v[28:29]
	v_mul_f32_e32 v25, v58, v25
	v_mul_f32_e32 v26, v59, v26
	v_cndmask_b32_e64 v59, v114, v99, s[4:5]
	v_cndmask_b32_e64 v58, v110, v98, s[4:5]
	v_pk_fma_f32 v[28:29], v[40:41], v[74:75], v[28:29]
	v_pk_fma_f32 v[28:29], v[32:33], v[58:59], v[28:29]
	v_pk_add_f32 v[28:29], v[36:37], v[28:29]
	v_mov_b32_dpp v96, v72 row_ror:1 row_mask:0xf bank_mask:0xf
	v_mul_f32_e32 v58, v28, v28
	v_fmamk_f32 v58, v58, 0xbdd2d3e7, v232
	v_mul_f32_e32 v59, v29, v29
	v_mul_f32_e32 v58, v28, v58
	v_fmamk_f32 v59, v59, 0xbdd2d3e7, v232
	v_mov_b32_dpp v97, v73 row_ror:1 row_mask:0xf bank_mask:0xf
	v_exp_f32_e32 v58, v58
	v_mul_f32_e32 v59, v29, v59
	v_cvt_pk_bf16_f32 v25, v25, v26
	v_cndmask_b32_e64 v27, v97, v115, s[2:3]
	v_cndmask_b32_e64 v26, v96, v111, s[2:3]
	v_exp_f32_e32 v59, v59
	v_mov_b32_dpp v100, v16 row_ror:15 row_mask:0xf bank_mask:0xf
	v_mov_b32_dpp v101, v17 row_ror:15 row_mask:0xf bank_mask:0xf
	v_pk_mul_f32 v[26:27], v[46:47], v[26:27]
	v_cndmask_b32_e64 v31, v117, v101, s[4:5]
	v_cndmask_b32_e64 v30, v116, v100, s[4:5]
	v_pk_fma_f32 v[26:27], v[42:43], v[72:73], v[26:27]
	v_pk_fma_f32 v[26:27], v[34:35], v[30:31], v[26:27]
	v_add_f32_e32 v30, 1.0, v58
	v_rcp_f32_e32 v58, v30
	v_add_f32_e32 v30, 1.0, v59
	v_rcp_f32_e32 v59, v30
	v_pk_add_f32 v[30:31], v[38:39], v[26:27]
	v_mul_f32_e32 v26, v28, v58
	v_mul_f32_e32 v28, v30, v30
	v_mul_f32_e32 v27, v29, v59
	v_mul_f32_e32 v29, v31, v31
	v_fmamk_f32 v28, v28, 0xbdd2d3e7, v232
	v_fmamk_f32 v29, v29, 0xbdd2d3e7, v232
	v_mul_f32_e32 v28, v30, v28
	v_mul_f32_e32 v29, v31, v29
	v_exp_f32_e32 v28, v28
	v_exp_f32_e32 v29, v29
	v_mul_f32_e32 v26, v62, v26
	v_mul_f32_e32 v27, v63, v27
	v_add_f32_e32 v28, 1.0, v28
	v_add_f32_e32 v29, 1.0, v29
	v_rcp_f32_e32 v28, v28
	v_rcp_f32_e32 v29, v29
	v_cvt_pk_bf16_f32 v26, v26, v27
	v_mul_f32_e32 v27, v30, v28
	v_mul_f32_e32 v28, v31, v29
	v_mul_f32_e32 v27, v56, v27
	v_mul_f32_e32 v28, v57, v28
	v_mov_b32_dpp v56, v22 row_ror:1 row_mask:0xf bank_mask:0xf
	v_mov_b32_dpp v57, v23 row_ror:1 row_mask:0xf bank_mask:0xf
	v_cndmask_b32_e64 v73, v57, v89, s[2:3]
	v_cndmask_b32_e64 v72, v56, v88, s[2:3]
	v_mov_b32_dpp v58, v48 row_ror:15 row_mask:0xf bank_mask:0xf
	v_mov_b32_dpp v60, v49 row_ror:15 row_mask:0xf bank_mask:0xf
	v_pk_mul_f32 v[72:73], v[84:85], v[72:73]
; #define LAS __attribute__((address_space(3)))
; __device__ __forceinline__ unsigned cvt_pk_bf16(float lo, float hi) { unsigned r; asm volatile("v_cvt_pk_bf16_f32 %0, %1, %2" : "=v"(r) : "v"(lo), "v"(hi)); return r; }
; __device__ __forceinline__ float dpp_ror1(float v) { return __int_as_float(__builtin_amdgcn_update_dpp(0, __float_as_int(v), 0x121, 0xf, 0xf, false)); }
;     __device__ __forceinline__ void operator()(f32x4 (&acc)[2][2][4][2], const Unit& u, int wr, int wc, int fr, int fq) const {
;     ...
;         for (int ai = 0; ai < 2; ++ai) {
;             const int rb = 2 * ai + wr;
;             f32x4 Sprev[2], Scur[2], Tcur[2], Tnext[2];
; #pragma unroll
;             for (int n = 0; n < 2; ++n) { Sprev[n] = (rb > 0) ? *(const LAS f32x4*)(XL + (rb - 1) * 128 + cl + 4 * n) : (f32x4){0.f, 0.f, 0.f, 0.f};
; #pragma unroll
;                 for (int j = 0; j < 4; ++j) Tcur[n][j] = dpp_rol1(acc[ai][0][0][n][j]); }
;     ...
;             for (int m = 0; m < 4; ++m) {
; #pragma unroll
;                 for (int n = 0; n < 2; ++n) {
; #pragma unroll
;                     for (int j = 0; j < 4; ++j) Scur[n][j] = dpp_ror1(acc[ai][0][m][n][j]);
;                     if (m < 3) {
; #pragma unroll
;                         for (int j = 0; j < 4; ++j) Tnext[n][j] = dpp_rol1(acc[ai][0][m < 3 ? m + 1 : 3][n][j]);
;                     } else Tnext[n] = (rb < 3) ? *(const LAS f32x4*)(XF + (rb + 1) * 128 + cl + 4 * n) : (f32x4){0.f, 0.f, 0.f, 0.f};
;                 }
;                 const int row = row0 + ai * HALF + m * 16, lrow = row & 255;
;                 const bool edge = (lrow == 0) || (lrow == 255);
;                 u32x4 ow;
; #pragma unroll
;                 for (int n = 0; n < 2; ++n) {
;                     const f32x4 up = (fr == 0) ? Sprev[n] : Scur[n], dn = (fr == 15) ? Tnext[n] : Tcur[n];
;                     const f32x4 a = w0[n] * up + w1[n] * acc[ai][0][m][n] + w2[n] * dn + bb[n];
;                     const f32x4 uu = acc[ai][1][m][n];
;                     ow[2 * n] = cvt_pk_bf16(gelu_tanh(a[0]) * uu[0], gelu_tanh(a[1]) * uu[1]);
;                     ow[2 * n + 1] = cvt_pk_bf16(gelu_tanh(a[2]) * uu[2], gelu_tanh(a[3]) * uu[3]);
;                 }
;                 if (!edge) *(u32x4*)(ACT + (size_t)row * DFF + f0) = ow;
	v_mov_b32_dpp v59, v20 row_ror:1 row_mask:0xf bank_mask:0xf
	v_mov_b32_dpp v61, v21 row_ror:1 row_mask:0xf bank_mask:0xf
	v_cndmask_b32_e64 v89, v91, v60, s[4:5]
	v_cndmask_b32_e64 v88, v90, v58, s[4:5]
	v_pk_fma_f32 v[22:23], v[80:81], v[22:23], v[72:73]
	v_cndmask_b32_e64 v67, v61, v67, s[2:3]
	v_cndmask_b32_e64 v66, v59, v66, s[2:3]
	v_pk_fma_f32 v[22:23], v[68:69], v[88:89], v[22:23]
	v_pk_mul_f32 v[66:67], v[86:87], v[66:67]
	v_pk_add_f32 v[22:23], v[76:77], v[22:23]
	v_pk_fma_f32 v[20:21], v[82:83], v[20:21], v[66:67]
	v_mul_f32_e32 v66, v22, v22
	v_fmamk_f32 v66, v66, 0xbdd2d3e7, v232
	v_mul_f32_e32 v67, v23, v23
	v_mul_f32_e32 v66, v22, v66
	v_fmamk_f32 v67, v67, 0xbdd2d3e7, v232
	v_exp_f32_e32 v66, v66
	v_mul_f32_e32 v67, v23, v67
	v_exp_f32_e32 v67, v67
	v_add_f32_e32 v66, 1.0, v66
	v_rcp_f32_e32 v66, v66
	v_add_f32_e32 v67, 1.0, v67
	v_mov_b32_dpp v62, v50 row_ror:15 row_mask:0xf bank_mask:0xf
	v_mov_b32_dpp v63, v51 row_ror:15 row_mask:0xf bank_mask:0xf
	v_rcp_f32_e32 v67, v67
	v_cndmask_b32_e64 v75, v93, v63, s[4:5]
	v_cndmask_b32_e64 v74, v92, v62, s[4:5]
	v_pk_fma_f32 v[20:21], v[70:71], v[74:75], v[20:21]
	v_pk_mul_f32 v[12:13], v[12:13], v[198:199] op_sel_hi:[1,0]
	v_pk_add_f32 v[20:21], v[78:79], v[20:21]
	v_mul_f32_e32 v22, v22, v66
	v_mul_f32_e32 v12, v12, v22
	v_mul_f32_e32 v22, v23, v67
	v_mul_f32_e32 v23, v20, v20
	v_fmamk_f32 v23, v23, 0xbdd2d3e7, v232
	v_mul_f32_e32 v66, v21, v21
	v_mul_f32_e32 v23, v20, v23
	v_fmamk_f32 v66, v66, 0xbdd2d3e7, v232
	v_exp_f32_e32 v23, v23
	v_mul_f32_e32 v66, v21, v66
	v_exp_f32_e32 v66, v66
	v_readlane_b32 s14, v254, 15
	v_mul_f32_e32 v13, v13, v22
	v_add_f32_e32 v22, 1.0, v23
	v_readlane_b32 s15, v254, 16
	v_rcp_f32_e32 v22, v22
	v_add_f32_e32 v23, 1.0, v66
	v_add_u32_e32 v102, 0x90, v174
	v_mov_b64_e32 v[64:65], s[14:15]
	v_rcp_f32_e32 v23, v23
	v_cvt_pk_bf16_f32 v27, v27, v28
	v_mad_i64_i32 v[28:29], s[14:15], v102, s73, v[64:65]
	v_lshl_add_u64 v[28:29], v[28:29], 0, v[112:113]
	v_pk_mul_f32 v[14:15], v[14:15], v[198:199] op_sel_hi:[1,0]
	global_store_dwordx4 v[28:29], v[24:27], off
	v_cvt_pk_bf16_f32 v12, v12, v13
	v_mul_f32_e32 v13, v20, v22
	v_mul_f32_e32 v13, v14, v13
	v_mul_f32_e32 v14, v21, v23
	v_mov_b32_dpp v24, v18 row_ror:1 row_mask:0xf bank_mask:0xf
	v_mov_b32_dpp v25, v19 row_ror:1 row_mask:0xf bank_mask:0xf
	v_mov_b32_dpp v27, v16 row_ror:1 row_mask:0xf bank_mask:0xf
	v_mov_b32_dpp v29, v17 row_ror:1 row_mask:0xf bank_mask:0xf
	v_mul_f32_e32 v14, v15, v14
	v_cvt_pk_bf16_f32 v13, v13, v14
	v_cndmask_b32_e64 v15, v29, v97, s[2:3]
	v_cndmask_b32_e64 v14, v27, v96, s[2:3]
	v_cndmask_b32_e64 v21, v25, v95, s[2:3]
	v_cndmask_b32_e64 v20, v24, v94, s[2:3]
	v_mov_b32_dpp v26, v52 row_ror:15 row_mask:0xf bank_mask:0xf
	v_mov_b32_dpp v28, v53 row_ror:15 row_mask:0xf bank_mask:0xf
	v_pk_mul_f32 v[20:21], v[44:45], v[20:21]
	v_pk_mul_f32 v[14:15], v[46:47], v[14:15]
	v_cndmask_b32_e64 v67, v99, v28, s[4:5]
	v_cndmask_b32_e64 v66, v98, v26, s[4:5]
	v_pk_fma_f32 v[14:15], v[42:43], v[16:17], v[14:15]
	v_pk_fma_f32 v[16:17], v[40:41], v[18:19], v[20:21]
	v_pk_fma_f32 v[16:17], v[32:33], v[66:67], v[16:17]
	v_pk_add_f32 v[16:17], v[36:37], v[16:17]
	v_mov_b32_dpp v30, v54 row_ror:15 row_mask:0xf bank_mask:0xf
	v_mul_f32_e32 v18, v16, v16
	v_fmamk_f32 v18, v18, 0xbdd2d3e7, v232
	v_mul_f32_e32 v18, v16, v18
	v_mul_f32_e32 v19, v17, v17
	v_exp_f32_e32 v18, v18
	v_fmamk_f32 v19, v19, 0xbdd2d3e7, v232
	v_mul_f32_e32 v19, v17, v19
	v_exp_f32_e32 v19, v19
	v_mov_b32_dpp v31, v55 row_ror:15 row_mask:0xf bank_mask:0xf
	v_add_f32_e32 v18, 1.0, v18
	v_cndmask_b32_e64 v23, v101, v31, s[4:5]
	v_cndmask_b32_e64 v22, v100, v30, s[4:5]
	v_rcp_f32_e32 v20, v18
	v_pk_fma_f32 v[14:15], v[34:35], v[22:23], v[14:15]
	v_add_f32_e32 v18, 1.0, v19
	v_rcp_f32_e32 v21, v18
	v_pk_add_f32 v[18:19], v[38:39], v[14:15]
	v_mul_f32_e32 v14, v16, v20
	v_mul_f32_e32 v15, v18, v18
	v_fmamk_f32 v15, v15, 0xbdd2d3e7, v232
	v_mul_f32_e32 v16, v19, v19
	v_mul_f32_e32 v15, v18, v15
	v_fmamk_f32 v16, v16, 0xbdd2d3e7, v232
	v_exp_f32_e32 v15, v15
	v_mul_f32_e32 v16, v19, v16
	v_exp_f32_e32 v16, v16
	v_pk_mul_f32 v[8:9], v[8:9], v[198:199] op_sel_hi:[1,0]
	v_pk_mul_f32 v[10:11], v[10:11], v[198:199] op_sel_hi:[1,0]
	v_mul_f32_e32 v8, v8, v14
	v_mul_f32_e32 v14, v17, v21
	v_mul_f32_e32 v9, v9, v14
	v_add_f32_e32 v14, 1.0, v15
	v_rcp_f32_e32 v15, v14
	v_add_f32_e32 v14, 1.0, v16
	v_rcp_f32_e32 v16, v14
	v_cvt_pk_bf16_f32 v14, v8, v9
	v_mul_f32_e32 v8, v18, v15
	v_add_u32_e32 v102, 0xa0, v174
	v_mul_f32_e32 v9, v19, v16
	v_mul_f32_e32 v8, v10, v8
	v_mul_f32_e32 v9, v11, v9
	v_cvt_pk_bf16_f32 v15, v8, v9
	v_mad_i64_i32 v[8:9], s[14:15], v102, s73, v[64:65]
	v_lshl_add_u64 v[8:9], v[8:9], 0, v[112:113]
	global_store_dwordx4 v[8:9], v[12:15], off
	v_cndmask_b32_e64 v9, 0, 1, s[40:41]
	v_mov_b32_dpp v21, v48 row_ror:1 row_mask:0xf bank_mask:0xf
	v_mov_b32_dpp v22, v49 row_ror:1 row_mask:0xf bank_mask:0xf
	v_mov_b32_dpp v23, v50 row_ror:1 row_mask:0xf bank_mask:0xf
	v_mov_b32_dpp v64, v51 row_ror:1 row_mask:0xf bank_mask:0xf
	v_mov_b32_e32 v8, 0
	v_cmp_ne_u32_e64 s[14:15], 1, v9
	s_andn2_b64 vcc, exec, s[40:41]
	v_mov_b32_e32 v12, 0
	v_mov_b32_e32 v13, 0
	v_mov_b32_e32 v14, 0
	v_mov_b32_e32 v15, 0
	s_cbranch_vccnz .LBB0_2076
	ds_read_b128 v[12:15], v227 offset:512
